# G2 gating de-serialised: 16 gate loads per branch prefetched 8-deep into dead B-fragment regs (saddr form), counted vmcnt waits instead of vmcnt(0) per load
# speedup vs baseline: 1.0126x; 1.0093x over previous
; template <bool DEEP>
; __device__ __forceinline__ void gemm_core(const bf16_t* __restrict__ A, int lda, const bf16_t* __restrict__ Bt, int ldb,
;                                           int K, f32x4 (&acc)[4][4], char* smem) {
;   bf16_t* sA = (bf16_t*)smem;
;   bf16_t* sB = sA + 2 * 128 * LDS_STRIDE;
;   const int tid = otid(), lane = tid & 63, wave = tid >> 6;
;   const int wm = wave >> 1, wn = wave & 1;
;   const int lr = tid >> 3, lc = (tid & 7) * 8;
;   const bf16_t* ap = A + (size_t)lr * lda + lc;
;   const bf16_t* bp = Bt + (size_t)lr * ldb + lc;
;   const int nk = K >> 6;
;   const int fr = lane & 15, fq = (lane >> 4) * 8;
;   const int rswz = (fr >> 1) & 7, wswz = (lr >> 1) & 7;
;   const int fo0 = (((lane >> 4)) ^ rswz) * 8, fo1 = ((4 + (lane >> 4)) ^ rswz) * 8;
;   const bf16_t* cA0 = sA + (wm * 64 + fr) * LDS_STRIDE;
;   const bf16_t* cB0 = sB + (wn * 64 + fr) * LDS_STRIDE;
;   bf16_t* wA = sA + lr * LDS_STRIDE + (((tid & 7) ^ wswz) * 8);
;   bf16_t* wB = sB + lr * LDS_STRIDE + (((tid & 7) ^ wswz) * 8);
;   constexpr int BUF = 128 * LDS_STRIDE;
;     ...
;   u32x4 ra0[4], rb0[4];
;   GLOAD(ra0, rb0, 0);
;   if (DEEP) {
;     u32x4 ra1[4], rb1[4];
;     GLOAD(ra1, rb1, 1);
;     __syncthreads();
;     SWRITE(ra0, rb0, 0);
;     __syncthreads();
;     for (int kt = 0; kt < nk; kt += 2) {
;       { const int k2 = min(kt + 2, nk - 1); GLOAD(ra0, rb0, k2); }
;       mma_ktile(cA0, cB0, fo0, fo1, acc);
;       SWRITE(ra1, rb1, 1);
;       __syncthreads();
;       { const int k3 = min(kt + 3, nk - 1); GLOAD(ra1, rb1, k3); }
;       mma_ktile(cA0 + BUF, cB0 + BUF, fo0, fo1, acc);
;       if (kt + 2 < nk) { SWRITE(ra0, rb0, 0); }
;       __syncthreads();
;     }
;   } else {
;     __syncthreads();
;     SWRITE(ra0, rb0, 0);
;     __syncthreads();
;     for (int kt = 0; kt < nk; ++kt) {
;       const int cur = kt & 1;
;       { const int k1 = min(kt + 1, nk - 1); GLOAD(ra0, rb0, k1); }
;       mma_ktile(cA0 + cur * BUF, cB0 + cur * BUF, fo0, fo1, acc);
;       if (kt + 1 < nk) { SWRITE(ra0, rb0, cur ^ 1); }
;       __syncthreads();
;     }
; __device__ __forceinline__ void phase_gemm_merge(const Params& p, char* smem) {
;     ...
;     for (int b = 0; b < 3; ++b) {
;       f32x4 acc[4][4];
; #pragma unroll
;       for (int i = 0; i < 4; ++i)
; #pragma unroll
;         for (int j = 0; j < 4; ++j) acc[i][j] = (f32x4){0.f, 0.f, 0.f, 0.f};
.LBB0_21:
	v_mov_b32_e32 v128, v178
	s_mov_b32 s29, 0x237f8000
	v_ashrrev_i32_e32 v126, 3, v128
	v_mad_i64_i32 v[4:5], s[30:31], v126, s78, 0
	v_lshlrev_b32_e32 v6, 4, v128
	v_and_b32_e32 v6, 0x70, v6
	s_add_u32 s30, s13, s16
	v_ashrrev_i32_e32 v127, 31, v126
	v_or_b32_e32 v4, v4, v6
	s_addc_u32 s31, s28, s17
	v_lshl_add_u64 v[36:37], s[30:31], 0, v[4:5]
	v_lshlrev_b64 v[4:5], 10, v[126:127]
	s_add_u32 s30, s10, s14
	v_or_b32_e32 v4, v4, v6
	s_addc_u32 s31, s11, s15
	v_lshl_add_u64 v[32:33], s[30:31], 0, v[4:5]
	v_add_co_u32_e32 v38, vcc, s29, v32
	s_mov_b32 s29, 0x23800000
	s_nop 0
	v_addc_co_u32_e32 v39, vcc, 0, v33, vcc
	v_add_co_u32_e32 v40, vcc, s1, v36
	v_and_b32_e32 v4, 15, v128
	s_nop 0
	v_addc_co_u32_e32 v41, vcc, 0, v37, vcc
	v_add_co_u32_e32 v42, vcc, s29, v32
	v_lshrrev_b32_e32 v7, 1, v128
	s_nop 0
	v_addc_co_u32_e32 v43, vcc, 0, v33, vcc
	v_lshrrev_b32_e32 v5, 4, v128
	v_bfe_u32 v6, v128, 4, 2
	v_bfe_u32 v8, v128, 1, 3
	v_and_or_b32 v4, v7, s79, v4
	v_add_co_u32_e32 v44, vcc, s0, v36
	v_bitop3_b32 v127, v5, v8, 3 bitop3:0x6c
	v_bitop3_b32 v129, v6, v8, 4 bitop3:0x36
	v_lshlrev_b32_e32 v130, 7, v4
	v_xor_b32_e32 v131, v5, v128
	global_load_dwordx4 v[4:7], v[36:37], off
	v_addc_co_u32_e32 v45, vcc, 0, v37, vcc
	s_mov_b32 s29, 0x23808000
	global_load_dwordx4 v[8:11], v[38:39], off
	v_add_co_u32_e32 v46, vcc, s29, v32
	global_load_dwordx4 v[12:15], v[40:41], off
	s_nop 0
	v_addc_co_u32_e32 v47, vcc, 0, v33, vcc
	s_mov_b32 s29, 0x48000
	global_load_dwordx4 v[16:19], v[42:43], off
	v_add_co_u32_e32 v48, vcc, s29, v36
	global_load_dwordx4 v[20:23], v[44:45], off
	s_nop 0
	v_addc_co_u32_e32 v49, vcc, 0, v37, vcc
	s_mov_b32 s29, 0x23810000
	global_load_dwordx4 v[24:27], v[46:47], off
	v_add_co_u32_e32 v50, vcc, s29, v32
	global_load_dwordx4 v[28:31], v[48:49], off
	s_nop 0
	v_addc_co_u32_e32 v51, vcc, 0, v33, vcc
	global_load_dwordx4 v[32:35], v[50:51], off
	v_lshlrev_b32_e32 v131, 4, v131
	v_and_b32_e32 v131, 0x70, v131
	v_lshl_or_b32 v126, v126, 7, v131
	s_barrier
	s_add_u32 s30, s10, 0xcb20000
	s_addc_u32 s31, s11, 0
	v_lshlrev_b32_e32 v176, 4, v129
	v_or_b32_e32 v129, v130, v176
	s_add_u32 s16, s16, 0x400
	s_addc_u32 s17, s17, 0
	s_add_u32 s14, s14, 0x100000
	s_addc_u32 s15, s15, 0
	s_cmpk_eq_i32 s16, 0xc00
	s_waitcnt vmcnt(7)
	ds_write_b128 v126, v[4:7]
	s_waitcnt vmcnt(6)
	ds_write_b128 v126, v[8:11] offset:32768
	s_waitcnt vmcnt(5)
	ds_write_b128 v126, v[12:15] offset:4096
	s_waitcnt vmcnt(4)
	ds_write_b128 v126, v[16:19] offset:36864
	s_waitcnt vmcnt(3)
	ds_write_b128 v126, v[20:23] offset:8192
	s_waitcnt vmcnt(2)
	ds_write_b128 v126, v[24:27] offset:40960
	s_waitcnt vmcnt(1)
	ds_write_b128 v126, v[28:31] offset:12288
	s_waitcnt vmcnt(0)
	ds_write_b128 v126, v[32:35] offset:45056
	v_lshlrev_b32_e32 v4, 7, v128
	v_and_b32_e32 v131, 0x2780, v4
	s_waitcnt lgkmcnt(0)
	s_barrier
	global_load_dwordx4 v[4:7], v[36:37], off offset:128
	global_load_dwordx4 v[8:11], v[38:39], off offset:128
	global_load_dwordx4 v[12:15], v[40:41], off offset:128
	global_load_dwordx4 v[16:19], v[42:43], off offset:128
	global_load_dwordx4 v[20:23], v[44:45], off offset:128
	global_load_dwordx4 v[24:27], v[46:47], off offset:128
	global_load_dwordx4 v[28:31], v[48:49], off offset:128
	global_load_dwordx4 v[32:35], v[50:51], off offset:128
	v_lshlrev_b32_e32 v128, 4, v127
	v_or_b32_e32 v127, v130, v128
	v_or_b32_e32 v128, v131, v128
	ds_read_b128 v[132:135], v127
	ds_read_b128 v[136:139], v127 offset:2048
	ds_read_b128 v[140:143], v127 offset:4096
	ds_read_b128 v[144:147], v127 offset:6144
	ds_read_b128 v[148:151], v128 offset:32768
	ds_read_b128 v[152:155], v128 offset:34816
	ds_read_b128 v[156:159], v128 offset:36864
	ds_read_b128 v[160:163], v128 offset:38912
	v_or_b32_e32 v130, v131, v176
	s_waitcnt lgkmcnt(3)
	v_mfma_f32_16x16x32_bf16 v[164:167], v[148:151], v[132:135], 0
	s_waitcnt lgkmcnt(2)
	v_mfma_f32_16x16x32_bf16 v[168:171], v[152:155], v[132:135], 0
	s_waitcnt lgkmcnt(1)
	v_mfma_f32_16x16x32_bf16 v[172:175], v[156:159], v[132:135], 0
	s_waitcnt lgkmcnt(0)
	v_mfma_f32_16x16x32_bf16 v[132:135], v[160:163], v[132:135], 0
	v_mfma_f32_16x16x32_bf16 v[188:191], v[148:151], v[136:139], 0
	v_mfma_f32_16x16x32_bf16 v[192:195], v[152:155], v[136:139], 0
	v_mfma_f32_16x16x32_bf16 v[196:199], v[156:159], v[136:139], 0
	v_mfma_f32_16x16x32_bf16 v[136:139], v[160:163], v[136:139], 0
	v_mfma_f32_16x16x32_bf16 v[200:203], v[148:151], v[140:143], 0
	v_mfma_f32_16x16x32_bf16 v[204:207], v[152:155], v[140:143], 0
	v_mfma_f32_16x16x32_bf16 v[208:211], v[156:159], v[140:143], 0
	v_mfma_f32_16x16x32_bf16 v[140:143], v[160:163], v[140:143], 0
	v_mfma_f32_16x16x32_bf16 v[148:151], v[148:151], v[144:147], 0
	v_mfma_f32_16x16x32_bf16 v[152:155], v[152:155], v[144:147], 0
	v_mfma_f32_16x16x32_bf16 v[156:159], v[156:159], v[144:147], 0
	v_mfma_f32_16x16x32_bf16 v[144:147], v[160:163], v[144:147], 0
	ds_read_b128 v[160:163], v129
	ds_read_b128 v[212:215], v129 offset:2048
	ds_read_b128 v[216:219], v129 offset:4096
	ds_read_b128 v[220:223], v129 offset:6144
	ds_read_b128 v[224:227], v130 offset:32768
	ds_read_b128 v[228:231], v130 offset:34816
	ds_read_b128 v[232:235], v130 offset:36864
	ds_read_b128 v[236:239], v130 offset:38912
	s_waitcnt vmcnt(7)
	ds_write_b128 v126, v[4:7] offset:16384
	s_waitcnt vmcnt(6)
	ds_write_b128 v126, v[8:11] offset:49152
	s_waitcnt vmcnt(5)
	ds_write_b128 v126, v[12:15] offset:20480
	s_waitcnt vmcnt(4)
	ds_write_b128 v126, v[16:19] offset:53248
	s_waitcnt vmcnt(3)
	ds_write_b128 v126, v[20:23] offset:24576
	s_waitcnt vmcnt(2)
	ds_write_b128 v126, v[24:27] offset:57344
	s_waitcnt vmcnt(1)
	ds_write_b128 v126, v[28:31] offset:28672
	s_waitcnt vmcnt(0)
	ds_write_b128 v126, v[32:35] offset:61440
	s_waitcnt lgkmcnt(0)
	s_barrier
; #define GLOAD(RA, RB, kt_)                                                         \
;   _Pragma("unroll") for (int i = 0; i < 4; ++i) {                                  \
;     RA[i] = *(const u32x4*)(ap + (size_t)(32 * i) * lda + ((kt_) << 6));           \
;     RB[i] = *(const u32x4*)(bp + (size_t)(32 * i) * ldb + ((kt_) << 6));           \
;   }
; #define SWRITE(RA, RB, buf_)                                                       \
;   _Pragma("unroll") for (int i = 0; i < 4; ++i) {                                  \
;     *(u32x4*)(wA + (buf_) * BUF + 32 * i * LDS_STRIDE) = RA[i];                    \
;     *(u32x4*)(wB + (buf_) * BUF + 32 * i * LDS_STRIDE) = RB[i];                    \
;   }
; __device__ __forceinline__ void mma_ktile(const bf16_t* cA, const bf16_t* cB, int fo0, int fo1, f32x4 (&acc)[4][4]) {
; #pragma unroll
;   for (int ks = 0; ks < 2; ++ks) {
;     const int fo = ks ? fo1 : fo0;
;     bf16x8 af[4], bfr[4];
; #pragma unroll
;     for (int i = 0; i < 4; ++i) af[i] = *(const bf16x8*)(cA + i * 16 * LDS_STRIDE + fo);
; #pragma unroll
;     for (int j = 0; j < 4; ++j) bfr[j] = *(const bf16x8*)(cB + j * 16 * LDS_STRIDE + fo);
; #pragma unroll
;     for (int i = 0; i < 4; ++i)
; #pragma unroll
;       for (int j = 0; j < 4; ++j)
;         acc[i][j] = __builtin_amdgcn_mfma_f32_16x16x32_bf16(bfr[j], af[i], acc[i][j], 0, 0, 0);
;   }
; }
; template <bool DEEP>
; __device__ __forceinline__ void gemm_core(const bf16_t* __restrict__ A, int lda, const bf16_t* __restrict__ Bt, int ldb,
;                                           int K, f32x4 (&acc)[4][4], char* smem) {
;     ...
;     __syncthreads();
;     SWRITE(ra0, rb0, 0);
;     __syncthreads();
;     for (int kt = 0; kt < nk; ++kt) {
;       const int cur = kt & 1;
;       { const int k1 = min(kt + 1, nk - 1); GLOAD(ra0, rb0, k1); }
;       mma_ktile(cA0 + cur * BUF, cB0 + cur * BUF, fo0, fo1, acc);
;       if (kt + 1 < nk) { SWRITE(ra0, rb0, cur ^ 1); }
;       __syncthreads();
;     }
	global_load_dwordx4 v[4:7], v[36:37], off offset:256
	global_load_dwordx4 v[8:11], v[38:39], off offset:256
	global_load_dwordx4 v[12:15], v[40:41], off offset:256
	global_load_dwordx4 v[16:19], v[42:43], off offset:256
	global_load_dwordx4 v[20:23], v[44:45], off offset:256
	global_load_dwordx4 v[24:27], v[46:47], off offset:256
	global_load_dwordx4 v[28:31], v[48:49], off offset:256
	global_load_dwordx4 v[32:35], v[50:51], off offset:256
	v_mfma_f32_16x16x32_bf16 v[164:167], v[224:227], v[160:163], v[164:167]
	v_mfma_f32_16x16x32_bf16 v[168:171], v[228:231], v[160:163], v[168:171]
	v_mfma_f32_16x16x32_bf16 v[172:175], v[232:235], v[160:163], v[172:175]
	v_mfma_f32_16x16x32_bf16 v[132:135], v[236:239], v[160:163], v[132:135]
	v_mfma_f32_16x16x32_bf16 v[160:163], v[224:227], v[212:215], v[188:191]
	v_mfma_f32_16x16x32_bf16 v[188:191], v[228:231], v[212:215], v[192:195]
	v_mfma_f32_16x16x32_bf16 v[192:195], v[232:235], v[212:215], v[196:199]
	v_mfma_f32_16x16x32_bf16 v[136:139], v[236:239], v[212:215], v[136:139]
	v_mfma_f32_16x16x32_bf16 v[196:199], v[224:227], v[216:219], v[200:203]
	v_mfma_f32_16x16x32_bf16 v[200:203], v[228:231], v[216:219], v[204:207]
	v_mfma_f32_16x16x32_bf16 v[204:207], v[232:235], v[216:219], v[208:211]
	v_mfma_f32_16x16x32_bf16 v[140:143], v[236:239], v[216:219], v[140:143]
	v_mfma_f32_16x16x32_bf16 v[148:151], v[224:227], v[220:223], v[148:151]
	v_mfma_f32_16x16x32_bf16 v[152:155], v[228:231], v[220:223], v[152:155]
	v_mfma_f32_16x16x32_bf16 v[156:159], v[232:235], v[220:223], v[156:159]
	v_mfma_f32_16x16x32_bf16 v[144:147], v[236:239], v[220:223], v[144:147]
	ds_read_b128 v[208:211], v127 offset:16384
	ds_read_b128 v[212:215], v127 offset:18432
	ds_read_b128 v[216:219], v127 offset:20480
	ds_read_b128 v[220:223], v127 offset:22528
	ds_read_b128 v[224:227], v128 offset:49152
	ds_read_b128 v[228:231], v128 offset:51200
	ds_read_b128 v[232:235], v128 offset:53248
	ds_read_b128 v[236:239], v128 offset:55296
	s_waitcnt lgkmcnt(3)
	v_mfma_f32_16x16x32_bf16 v[164:167], v[224:227], v[208:211], v[164:167]
	s_waitcnt lgkmcnt(2)
	v_mfma_f32_16x16x32_bf16 v[168:171], v[228:231], v[208:211], v[168:171]
	s_waitcnt lgkmcnt(1)
	v_mfma_f32_16x16x32_bf16 v[172:175], v[232:235], v[208:211], v[172:175]
	s_waitcnt lgkmcnt(0)
	v_mfma_f32_16x16x32_bf16 v[132:135], v[236:239], v[208:211], v[132:135]
	v_mfma_f32_16x16x32_bf16 v[160:163], v[224:227], v[212:215], v[160:163]
	v_mfma_f32_16x16x32_bf16 v[188:191], v[228:231], v[212:215], v[188:191]
	v_mfma_f32_16x16x32_bf16 v[192:195], v[232:235], v[212:215], v[192:195]
	v_mfma_f32_16x16x32_bf16 v[136:139], v[236:239], v[212:215], v[136:139]
	v_mfma_f32_16x16x32_bf16 v[196:199], v[224:227], v[216:219], v[196:199]
	v_mfma_f32_16x16x32_bf16 v[200:203], v[228:231], v[216:219], v[200:203]
	v_mfma_f32_16x16x32_bf16 v[204:207], v[232:235], v[216:219], v[204:207]
	v_mfma_f32_16x16x32_bf16 v[140:143], v[236:239], v[216:219], v[140:143]
	v_mfma_f32_16x16x32_bf16 v[148:151], v[224:227], v[220:223], v[148:151]
	v_mfma_f32_16x16x32_bf16 v[152:155], v[228:231], v[220:223], v[152:155]
	v_mfma_f32_16x16x32_bf16 v[156:159], v[232:235], v[220:223], v[156:159]
	v_mfma_f32_16x16x32_bf16 v[144:147], v[236:239], v[220:223], v[144:147]
	ds_read_b128 v[208:211], v129 offset:16384
	ds_read_b128 v[212:215], v129 offset:18432
	ds_read_b128 v[216:219], v129 offset:20480
	ds_read_b128 v[220:223], v129 offset:22528
	ds_read_b128 v[224:227], v130 offset:49152
	ds_read_b128 v[228:231], v130 offset:51200
	ds_read_b128 v[232:235], v130 offset:53248
	ds_read_b128 v[236:239], v130 offset:55296
	s_waitcnt vmcnt(7)
	ds_write_b128 v126, v[4:7]
	s_waitcnt vmcnt(6)
	ds_write_b128 v126, v[8:11] offset:32768
	s_waitcnt vmcnt(5)
	ds_write_b128 v126, v[12:15] offset:4096
	s_waitcnt vmcnt(4)
	ds_write_b128 v126, v[16:19] offset:36864
	s_waitcnt vmcnt(3)
	ds_write_b128 v126, v[20:23] offset:8192
	s_waitcnt vmcnt(2)
	ds_write_b128 v126, v[24:27] offset:40960
	s_waitcnt vmcnt(1)
	ds_write_b128 v126, v[28:31] offset:12288
	s_waitcnt vmcnt(0)
	ds_write_b128 v126, v[32:35] offset:45056
	s_waitcnt lgkmcnt(0)
	s_barrier
	global_load_dwordx4 v[4:7], v[36:37], off offset:384
	global_load_dwordx4 v[8:11], v[38:39], off offset:384
	global_load_dwordx4 v[12:15], v[40:41], off offset:384
	global_load_dwordx4 v[16:19], v[42:43], off offset:384
	global_load_dwordx4 v[20:23], v[44:45], off offset:384
	global_load_dwordx4 v[24:27], v[46:47], off offset:384
	global_load_dwordx4 v[28:31], v[48:49], off offset:384
	global_load_dwordx4 v[32:35], v[50:51], off offset:384
	v_mfma_f32_16x16x32_bf16 v[164:167], v[224:227], v[208:211], v[164:167]
	v_mfma_f32_16x16x32_bf16 v[168:171], v[228:231], v[208:211], v[168:171]
	v_mfma_f32_16x16x32_bf16 v[172:175], v[232:235], v[208:211], v[172:175]
	v_mfma_f32_16x16x32_bf16 v[132:135], v[236:239], v[208:211], v[132:135]
	v_mfma_f32_16x16x32_bf16 v[160:163], v[224:227], v[212:215], v[160:163]
	v_mfma_f32_16x16x32_bf16 v[188:191], v[228:231], v[212:215], v[188:191]
	v_mfma_f32_16x16x32_bf16 v[192:195], v[232:235], v[212:215], v[192:195]
	v_mfma_f32_16x16x32_bf16 v[136:139], v[236:239], v[212:215], v[136:139]
	v_mfma_f32_16x16x32_bf16 v[196:199], v[224:227], v[216:219], v[196:199]
	v_mfma_f32_16x16x32_bf16 v[200:203], v[228:231], v[216:219], v[200:203]
	v_mfma_f32_16x16x32_bf16 v[204:207], v[232:235], v[216:219], v[204:207]
	v_mfma_f32_16x16x32_bf16 v[140:143], v[236:239], v[216:219], v[140:143]
	v_mfma_f32_16x16x32_bf16 v[148:151], v[224:227], v[220:223], v[148:151]
	v_mfma_f32_16x16x32_bf16 v[152:155], v[228:231], v[220:223], v[152:155]
	v_mfma_f32_16x16x32_bf16 v[156:159], v[232:235], v[220:223], v[156:159]
	v_mfma_f32_16x16x32_bf16 v[144:147], v[236:239], v[220:223], v[144:147]
	ds_read_b128 v[208:211], v127
	ds_read_b128 v[212:215], v127 offset:2048
	ds_read_b128 v[216:219], v127 offset:4096
	ds_read_b128 v[220:223], v127 offset:6144
	ds_read_b128 v[224:227], v128 offset:32768
	ds_read_b128 v[228:231], v128 offset:34816
	ds_read_b128 v[232:235], v128 offset:36864
	ds_read_b128 v[236:239], v128 offset:38912
	s_waitcnt lgkmcnt(3)
; #define GLOAD(RA, RB, kt_)                                                         \
;   _Pragma("unroll") for (int i = 0; i < 4; ++i) {                                  \
;     RA[i] = *(const u32x4*)(ap + (size_t)(32 * i) * lda + ((kt_) << 6));           \
;     RB[i] = *(const u32x4*)(bp + (size_t)(32 * i) * ldb + ((kt_) << 6));           \
;   }
; #define SWRITE(RA, RB, buf_)                                                       \
;   _Pragma("unroll") for (int i = 0; i < 4; ++i) {                                  \
;     *(u32x4*)(wA + (buf_) * BUF + 32 * i * LDS_STRIDE) = RA[i];                    \
;     *(u32x4*)(wB + (buf_) * BUF + 32 * i * LDS_STRIDE) = RB[i];                    \
;   }
; __device__ __forceinline__ void mma_ktile(const bf16_t* cA, const bf16_t* cB, int fo0, int fo1, f32x4 (&acc)[4][4]) {
; #pragma unroll
;   for (int ks = 0; ks < 2; ++ks) {
;     const int fo = ks ? fo1 : fo0;
;     bf16x8 af[4], bfr[4];
; #pragma unroll
;     for (int i = 0; i < 4; ++i) af[i] = *(const bf16x8*)(cA + i * 16 * LDS_STRIDE + fo);
; #pragma unroll
;     for (int j = 0; j < 4; ++j) bfr[j] = *(const bf16x8*)(cB + j * 16 * LDS_STRIDE + fo);
; #pragma unroll
;     for (int i = 0; i < 4; ++i)
; #pragma unroll
;       for (int j = 0; j < 4; ++j)
;         acc[i][j] = __builtin_amdgcn_mfma_f32_16x16x32_bf16(bfr[j], af[i], acc[i][j], 0, 0, 0);
;   }
; }
; template <bool DEEP>
; __device__ __forceinline__ void gemm_core(const bf16_t* __restrict__ A, int lda, const bf16_t* __restrict__ Bt, int ldb,
;                                           int K, f32x4 (&acc)[4][4], char* smem) {
;     ...
;     __syncthreads();
;     SWRITE(ra0, rb0, 0);
;     __syncthreads();
;     for (int kt = 0; kt < nk; ++kt) {
;       const int cur = kt & 1;
;       { const int k1 = min(kt + 1, nk - 1); GLOAD(ra0, rb0, k1); }
;       mma_ktile(cA0 + cur * BUF, cB0 + cur * BUF, fo0, fo1, acc);
;       if (kt + 1 < nk) { SWRITE(ra0, rb0, cur ^ 1); }
;       __syncthreads();
;     }
	v_mfma_f32_16x16x32_bf16 v[164:167], v[224:227], v[208:211], v[164:167]
	s_waitcnt lgkmcnt(2)
	v_mfma_f32_16x16x32_bf16 v[168:171], v[228:231], v[208:211], v[168:171]
	s_waitcnt lgkmcnt(1)
	v_mfma_f32_16x16x32_bf16 v[172:175], v[232:235], v[208:211], v[172:175]
	s_waitcnt lgkmcnt(0)
	v_mfma_f32_16x16x32_bf16 v[132:135], v[236:239], v[208:211], v[132:135]
	v_mfma_f32_16x16x32_bf16 v[160:163], v[224:227], v[212:215], v[160:163]
	v_mfma_f32_16x16x32_bf16 v[188:191], v[228:231], v[212:215], v[188:191]
	v_mfma_f32_16x16x32_bf16 v[192:195], v[232:235], v[212:215], v[192:195]
	v_mfma_f32_16x16x32_bf16 v[136:139], v[236:239], v[212:215], v[136:139]
	v_mfma_f32_16x16x32_bf16 v[196:199], v[224:227], v[216:219], v[196:199]
	v_mfma_f32_16x16x32_bf16 v[200:203], v[228:231], v[216:219], v[200:203]
	v_mfma_f32_16x16x32_bf16 v[204:207], v[232:235], v[216:219], v[204:207]
	v_mfma_f32_16x16x32_bf16 v[140:143], v[236:239], v[216:219], v[140:143]
	v_mfma_f32_16x16x32_bf16 v[148:151], v[224:227], v[220:223], v[148:151]
	v_mfma_f32_16x16x32_bf16 v[152:155], v[228:231], v[220:223], v[152:155]
	v_mfma_f32_16x16x32_bf16 v[156:159], v[232:235], v[220:223], v[156:159]
	v_mfma_f32_16x16x32_bf16 v[144:147], v[236:239], v[220:223], v[144:147]
	ds_read_b128 v[208:211], v129
	ds_read_b128 v[212:215], v129 offset:2048
	ds_read_b128 v[216:219], v129 offset:4096
	ds_read_b128 v[220:223], v129 offset:6144
	ds_read_b128 v[224:227], v130 offset:32768
	ds_read_b128 v[228:231], v130 offset:34816
	ds_read_b128 v[232:235], v130 offset:36864
	ds_read_b128 v[236:239], v130 offset:38912
	s_waitcnt vmcnt(7)
	ds_write_b128 v126, v[4:7] offset:16384
	s_waitcnt vmcnt(6)
	ds_write_b128 v126, v[8:11] offset:49152
	s_waitcnt vmcnt(5)
	ds_write_b128 v126, v[12:15] offset:20480
	s_waitcnt vmcnt(4)
	ds_write_b128 v126, v[16:19] offset:53248
	s_waitcnt vmcnt(3)
	ds_write_b128 v126, v[20:23] offset:24576
	s_waitcnt vmcnt(2)
	ds_write_b128 v126, v[24:27] offset:57344
	s_waitcnt vmcnt(1)
	ds_write_b128 v126, v[28:31] offset:28672
	s_waitcnt vmcnt(0)
	ds_write_b128 v126, v[32:35] offset:61440
	s_waitcnt lgkmcnt(0)
	s_barrier
	global_load_dwordx4 v[4:7], v[36:37], off offset:512
	global_load_dwordx4 v[8:11], v[38:39], off offset:512
	global_load_dwordx4 v[12:15], v[40:41], off offset:512
	global_load_dwordx4 v[16:19], v[42:43], off offset:512
	global_load_dwordx4 v[20:23], v[44:45], off offset:512
	global_load_dwordx4 v[24:27], v[46:47], off offset:512
	global_load_dwordx4 v[28:31], v[48:49], off offset:512
	global_load_dwordx4 v[32:35], v[50:51], off offset:512
	v_mfma_f32_16x16x32_bf16 v[164:167], v[224:227], v[208:211], v[164:167]
	v_mfma_f32_16x16x32_bf16 v[168:171], v[228:231], v[208:211], v[168:171]
	v_mfma_f32_16x16x32_bf16 v[172:175], v[232:235], v[208:211], v[172:175]
	v_mfma_f32_16x16x32_bf16 v[132:135], v[236:239], v[208:211], v[132:135]
	v_mfma_f32_16x16x32_bf16 v[160:163], v[224:227], v[212:215], v[160:163]
	v_mfma_f32_16x16x32_bf16 v[188:191], v[228:231], v[212:215], v[188:191]
	v_mfma_f32_16x16x32_bf16 v[192:195], v[232:235], v[212:215], v[192:195]
	v_mfma_f32_16x16x32_bf16 v[136:139], v[236:239], v[212:215], v[136:139]
	v_mfma_f32_16x16x32_bf16 v[196:199], v[224:227], v[216:219], v[196:199]
	v_mfma_f32_16x16x32_bf16 v[200:203], v[228:231], v[216:219], v[200:203]
	v_mfma_f32_16x16x32_bf16 v[204:207], v[232:235], v[216:219], v[204:207]
	v_mfma_f32_16x16x32_bf16 v[140:143], v[236:239], v[216:219], v[140:143]
	v_mfma_f32_16x16x32_bf16 v[148:151], v[224:227], v[220:223], v[148:151]
	v_mfma_f32_16x16x32_bf16 v[152:155], v[228:231], v[220:223], v[152:155]
	v_mfma_f32_16x16x32_bf16 v[156:159], v[232:235], v[220:223], v[156:159]
	v_mfma_f32_16x16x32_bf16 v[144:147], v[236:239], v[220:223], v[144:147]
	ds_read_b128 v[208:211], v127 offset:16384
	ds_read_b128 v[212:215], v127 offset:18432
	ds_read_b128 v[216:219], v127 offset:20480
	ds_read_b128 v[220:223], v127 offset:22528
	ds_read_b128 v[224:227], v128 offset:49152
	ds_read_b128 v[228:231], v128 offset:51200
	ds_read_b128 v[232:235], v128 offset:53248
	ds_read_b128 v[236:239], v128 offset:55296
	s_waitcnt lgkmcnt(3)
	v_mfma_f32_16x16x32_bf16 v[164:167], v[224:227], v[208:211], v[164:167]
	s_waitcnt lgkmcnt(2)
	v_mfma_f32_16x16x32_bf16 v[168:171], v[228:231], v[208:211], v[168:171]
	s_waitcnt lgkmcnt(1)
	v_mfma_f32_16x16x32_bf16 v[172:175], v[232:235], v[208:211], v[172:175]
	s_waitcnt lgkmcnt(0)
	v_mfma_f32_16x16x32_bf16 v[132:135], v[236:239], v[208:211], v[132:135]
	v_mfma_f32_16x16x32_bf16 v[160:163], v[224:227], v[212:215], v[160:163]
	v_mfma_f32_16x16x32_bf16 v[188:191], v[228:231], v[212:215], v[188:191]
	v_mfma_f32_16x16x32_bf16 v[192:195], v[232:235], v[212:215], v[192:195]
	v_mfma_f32_16x16x32_bf16 v[136:139], v[236:239], v[212:215], v[136:139]
	v_mfma_f32_16x16x32_bf16 v[196:199], v[224:227], v[216:219], v[196:199]
	v_mfma_f32_16x16x32_bf16 v[200:203], v[228:231], v[216:219], v[200:203]
	v_mfma_f32_16x16x32_bf16 v[204:207], v[232:235], v[216:219], v[204:207]
	v_mfma_f32_16x16x32_bf16 v[140:143], v[236:239], v[216:219], v[140:143]
	v_mfma_f32_16x16x32_bf16 v[148:151], v[224:227], v[220:223], v[148:151]
	v_mfma_f32_16x16x32_bf16 v[152:155], v[228:231], v[220:223], v[152:155]
	v_mfma_f32_16x16x32_bf16 v[156:159], v[232:235], v[220:223], v[156:159]
	v_mfma_f32_16x16x32_bf16 v[144:147], v[236:239], v[220:223], v[144:147]
	ds_read_b128 v[208:211], v129 offset:16384
	ds_read_b128 v[212:215], v129 offset:18432
	ds_read_b128 v[216:219], v129 offset:20480
	ds_read_b128 v[220:223], v129 offset:22528
	ds_read_b128 v[224:227], v130 offset:49152
	ds_read_b128 v[228:231], v130 offset:51200
	ds_read_b128 v[232:235], v130 offset:53248
	ds_read_b128 v[236:239], v130 offset:55296
	s_waitcnt vmcnt(7)
	ds_write_b128 v126, v[4:7]
	s_waitcnt vmcnt(6)
	ds_write_b128 v126, v[8:11] offset:32768
	s_waitcnt vmcnt(5)
	ds_write_b128 v126, v[12:15] offset:4096
	s_waitcnt vmcnt(4)
	ds_write_b128 v126, v[16:19] offset:36864
	s_waitcnt vmcnt(3)
	ds_write_b128 v126, v[20:23] offset:8192
	s_waitcnt vmcnt(2)
	ds_write_b128 v126, v[24:27] offset:40960
	s_waitcnt vmcnt(1)
	ds_write_b128 v126, v[28:31] offset:12288
	s_waitcnt vmcnt(0)
	ds_write_b128 v126, v[32:35] offset:45056
	s_waitcnt lgkmcnt(0)
	s_barrier
; #define GLOAD(RA, RB, kt_)                                                         \
;   _Pragma("unroll") for (int i = 0; i < 4; ++i) {                                  \
;     RA[i] = *(const u32x4*)(ap + (size_t)(32 * i) * lda + ((kt_) << 6));           \
;     RB[i] = *(const u32x4*)(bp + (size_t)(32 * i) * ldb + ((kt_) << 6));           \
;   }
; #define SWRITE(RA, RB, buf_)                                                       \
;   _Pragma("unroll") for (int i = 0; i < 4; ++i) {                                  \
;     *(u32x4*)(wA + (buf_) * BUF + 32 * i * LDS_STRIDE) = RA[i];                    \
;     *(u32x4*)(wB + (buf_) * BUF + 32 * i * LDS_STRIDE) = RB[i];                    \
;   }
; __device__ __forceinline__ void mma_ktile(const bf16_t* cA, const bf16_t* cB, int fo0, int fo1, f32x4 (&acc)[4][4]) {
; #pragma unroll
;   for (int ks = 0; ks < 2; ++ks) {
;     const int fo = ks ? fo1 : fo0;
;     bf16x8 af[4], bfr[4];
; #pragma unroll
;     for (int i = 0; i < 4; ++i) af[i] = *(const bf16x8*)(cA + i * 16 * LDS_STRIDE + fo);
; #pragma unroll
;     for (int j = 0; j < 4; ++j) bfr[j] = *(const bf16x8*)(cB + j * 16 * LDS_STRIDE + fo);
; #pragma unroll
;     for (int i = 0; i < 4; ++i)
; #pragma unroll
;       for (int j = 0; j < 4; ++j)
;         acc[i][j] = __builtin_amdgcn_mfma_f32_16x16x32_bf16(bfr[j], af[i], acc[i][j], 0, 0, 0);
;   }
; }
; template <bool DEEP>
; __device__ __forceinline__ void gemm_core(const bf16_t* __restrict__ A, int lda, const bf16_t* __restrict__ Bt, int ldb,
;                                           int K, f32x4 (&acc)[4][4], char* smem) {
;     ...
;     __syncthreads();
;     SWRITE(ra0, rb0, 0);
;     __syncthreads();
;     for (int kt = 0; kt < nk; ++kt) {
;       const int cur = kt & 1;
;       { const int k1 = min(kt + 1, nk - 1); GLOAD(ra0, rb0, k1); }
;       mma_ktile(cA0 + cur * BUF, cB0 + cur * BUF, fo0, fo1, acc);
;       if (kt + 1 < nk) { SWRITE(ra0, rb0, cur ^ 1); }
;       __syncthreads();
;     }
	global_load_dwordx4 v[4:7], v[36:37], off offset:640
	global_load_dwordx4 v[8:11], v[38:39], off offset:640
	global_load_dwordx4 v[12:15], v[40:41], off offset:640
	global_load_dwordx4 v[16:19], v[42:43], off offset:640
	global_load_dwordx4 v[20:23], v[44:45], off offset:640
	global_load_dwordx4 v[24:27], v[46:47], off offset:640
	global_load_dwordx4 v[28:31], v[48:49], off offset:640
	global_load_dwordx4 v[32:35], v[50:51], off offset:640
	v_mfma_f32_16x16x32_bf16 v[164:167], v[224:227], v[208:211], v[164:167]
	v_mfma_f32_16x16x32_bf16 v[168:171], v[228:231], v[208:211], v[168:171]
	v_mfma_f32_16x16x32_bf16 v[172:175], v[232:235], v[208:211], v[172:175]
	v_mfma_f32_16x16x32_bf16 v[132:135], v[236:239], v[208:211], v[132:135]
	v_mfma_f32_16x16x32_bf16 v[160:163], v[224:227], v[212:215], v[160:163]
	v_mfma_f32_16x16x32_bf16 v[188:191], v[228:231], v[212:215], v[188:191]
	v_mfma_f32_16x16x32_bf16 v[192:195], v[232:235], v[212:215], v[192:195]
	v_mfma_f32_16x16x32_bf16 v[136:139], v[236:239], v[212:215], v[136:139]
	v_mfma_f32_16x16x32_bf16 v[196:199], v[224:227], v[216:219], v[196:199]
	v_mfma_f32_16x16x32_bf16 v[200:203], v[228:231], v[216:219], v[200:203]
	v_mfma_f32_16x16x32_bf16 v[204:207], v[232:235], v[216:219], v[204:207]
	v_mfma_f32_16x16x32_bf16 v[140:143], v[236:239], v[216:219], v[140:143]
	v_mfma_f32_16x16x32_bf16 v[148:151], v[224:227], v[220:223], v[148:151]
	v_mfma_f32_16x16x32_bf16 v[152:155], v[228:231], v[220:223], v[152:155]
	v_mfma_f32_16x16x32_bf16 v[156:159], v[232:235], v[220:223], v[156:159]
	v_mfma_f32_16x16x32_bf16 v[144:147], v[236:239], v[220:223], v[144:147]
	ds_read_b128 v[208:211], v127
	ds_read_b128 v[212:215], v127 offset:2048
	ds_read_b128 v[216:219], v127 offset:4096
	ds_read_b128 v[220:223], v127 offset:6144
	ds_read_b128 v[224:227], v128 offset:32768
	ds_read_b128 v[228:231], v128 offset:34816
	ds_read_b128 v[232:235], v128 offset:36864
	ds_read_b128 v[236:239], v128 offset:38912
	s_waitcnt lgkmcnt(3)
	v_mfma_f32_16x16x32_bf16 v[164:167], v[224:227], v[208:211], v[164:167]
	s_waitcnt lgkmcnt(2)
	v_mfma_f32_16x16x32_bf16 v[168:171], v[228:231], v[208:211], v[168:171]
	s_waitcnt lgkmcnt(1)
	v_mfma_f32_16x16x32_bf16 v[172:175], v[232:235], v[208:211], v[172:175]
	s_waitcnt lgkmcnt(0)
	v_mfma_f32_16x16x32_bf16 v[132:135], v[236:239], v[208:211], v[132:135]
	v_mfma_f32_16x16x32_bf16 v[160:163], v[224:227], v[212:215], v[160:163]
	v_mfma_f32_16x16x32_bf16 v[188:191], v[228:231], v[212:215], v[188:191]
	v_mfma_f32_16x16x32_bf16 v[192:195], v[232:235], v[212:215], v[192:195]
	v_mfma_f32_16x16x32_bf16 v[136:139], v[236:239], v[212:215], v[136:139]
	v_mfma_f32_16x16x32_bf16 v[196:199], v[224:227], v[216:219], v[196:199]
	v_mfma_f32_16x16x32_bf16 v[200:203], v[228:231], v[216:219], v[200:203]
	v_mfma_f32_16x16x32_bf16 v[204:207], v[232:235], v[216:219], v[204:207]
	v_mfma_f32_16x16x32_bf16 v[140:143], v[236:239], v[216:219], v[140:143]
	v_mfma_f32_16x16x32_bf16 v[148:151], v[224:227], v[220:223], v[148:151]
	v_mfma_f32_16x16x32_bf16 v[152:155], v[228:231], v[220:223], v[152:155]
	v_mfma_f32_16x16x32_bf16 v[156:159], v[232:235], v[220:223], v[156:159]
	v_mfma_f32_16x16x32_bf16 v[144:147], v[236:239], v[220:223], v[144:147]
	ds_read_b128 v[208:211], v129
	ds_read_b128 v[212:215], v129 offset:2048
	ds_read_b128 v[216:219], v129 offset:4096
	ds_read_b128 v[220:223], v129 offset:6144
	ds_read_b128 v[224:227], v130 offset:32768
	ds_read_b128 v[228:231], v130 offset:34816
	ds_read_b128 v[232:235], v130 offset:36864
	ds_read_b128 v[236:239], v130 offset:38912
	s_waitcnt vmcnt(7)
	ds_write_b128 v126, v[4:7] offset:16384
	s_waitcnt vmcnt(6)
	ds_write_b128 v126, v[8:11] offset:49152
	s_waitcnt vmcnt(5)
	ds_write_b128 v126, v[12:15] offset:20480
	s_waitcnt vmcnt(4)
	ds_write_b128 v126, v[16:19] offset:53248
	s_waitcnt vmcnt(3)
	ds_write_b128 v126, v[20:23] offset:24576
	s_waitcnt vmcnt(2)
	ds_write_b128 v126, v[24:27] offset:57344
	s_waitcnt vmcnt(1)
	ds_write_b128 v126, v[28:31] offset:28672
	s_waitcnt vmcnt(0)
	ds_write_b128 v126, v[32:35] offset:61440
	s_waitcnt lgkmcnt(0)
	s_barrier
	global_load_dwordx4 v[4:7], v[36:37], off offset:768
	global_load_dwordx4 v[8:11], v[38:39], off offset:768
	global_load_dwordx4 v[12:15], v[40:41], off offset:768
	global_load_dwordx4 v[16:19], v[42:43], off offset:768
	global_load_dwordx4 v[20:23], v[44:45], off offset:768
	global_load_dwordx4 v[24:27], v[46:47], off offset:768
	global_load_dwordx4 v[28:31], v[48:49], off offset:768
	global_load_dwordx4 v[32:35], v[50:51], off offset:768
	v_mfma_f32_16x16x32_bf16 v[164:167], v[224:227], v[208:211], v[164:167]
	v_mfma_f32_16x16x32_bf16 v[168:171], v[228:231], v[208:211], v[168:171]
	v_mfma_f32_16x16x32_bf16 v[172:175], v[232:235], v[208:211], v[172:175]
	v_mfma_f32_16x16x32_bf16 v[132:135], v[236:239], v[208:211], v[132:135]
	v_mfma_f32_16x16x32_bf16 v[160:163], v[224:227], v[212:215], v[160:163]
	v_mfma_f32_16x16x32_bf16 v[188:191], v[228:231], v[212:215], v[188:191]
	v_mfma_f32_16x16x32_bf16 v[192:195], v[232:235], v[212:215], v[192:195]
	v_mfma_f32_16x16x32_bf16 v[136:139], v[236:239], v[212:215], v[136:139]
	v_mfma_f32_16x16x32_bf16 v[196:199], v[224:227], v[216:219], v[196:199]
	v_mfma_f32_16x16x32_bf16 v[200:203], v[228:231], v[216:219], v[200:203]
	v_mfma_f32_16x16x32_bf16 v[204:207], v[232:235], v[216:219], v[204:207]
	v_mfma_f32_16x16x32_bf16 v[140:143], v[236:239], v[216:219], v[140:143]
	v_mfma_f32_16x16x32_bf16 v[148:151], v[224:227], v[220:223], v[148:151]
	v_mfma_f32_16x16x32_bf16 v[152:155], v[228:231], v[220:223], v[152:155]
	v_mfma_f32_16x16x32_bf16 v[156:159], v[232:235], v[220:223], v[156:159]
	v_mfma_f32_16x16x32_bf16 v[144:147], v[236:239], v[220:223], v[144:147]
	ds_read_b128 v[208:211], v127 offset:16384
	ds_read_b128 v[212:215], v127 offset:18432
	ds_read_b128 v[216:219], v127 offset:20480
	ds_read_b128 v[220:223], v127 offset:22528
	ds_read_b128 v[224:227], v128 offset:49152
	ds_read_b128 v[228:231], v128 offset:51200
	ds_read_b128 v[232:235], v128 offset:53248
	ds_read_b128 v[236:239], v128 offset:55296
	s_waitcnt lgkmcnt(3)
; #define GLOAD(RA, RB, kt_)                                                         \
;   _Pragma("unroll") for (int i = 0; i < 4; ++i) {                                  \
;     RA[i] = *(const u32x4*)(ap + (size_t)(32 * i) * lda + ((kt_) << 6));           \
;     RB[i] = *(const u32x4*)(bp + (size_t)(32 * i) * ldb + ((kt_) << 6));           \
;   }
; #define SWRITE(RA, RB, buf_)                                                       \
;   _Pragma("unroll") for (int i = 0; i < 4; ++i) {                                  \
;     *(u32x4*)(wA + (buf_) * BUF + 32 * i * LDS_STRIDE) = RA[i];                    \
;     *(u32x4*)(wB + (buf_) * BUF + 32 * i * LDS_STRIDE) = RB[i];                    \
;   }
; template <bool DEEP>
; __device__ __forceinline__ void gemm_core(const bf16_t* __restrict__ A, int lda, const bf16_t* __restrict__ Bt, int ldb,
;                                           int K, f32x4 (&acc)[4][4], char* smem) {
;     ...
;     __syncthreads();
;     SWRITE(ra0, rb0, 0);
;     __syncthreads();
;     for (int kt = 0; kt < nk; ++kt) {
;       const int cur = kt & 1;
;       { const int k1 = min(kt + 1, nk - 1); GLOAD(ra0, rb0, k1); }
;       mma_ktile(cA0 + cur * BUF, cB0 + cur * BUF, fo0, fo1, acc);
;       if (kt + 1 < nk) { SWRITE(ra0, rb0, cur ^ 1); }
;       __syncthreads();
;     }
; __device__ __forceinline__ void phase_gemm_merge(const Params& p, char* smem) {
;     ...
;       for (int i = 0; i < 4; ++i) {
;         const int m = mt * 128 + wm * 64 + i * 16 + (lane & 15);
; #pragma unroll
;         for (int j = 0; j < 4; ++j) {
;           const int n = nt * 128 + wn * 64 + j * 16 + (lane >> 4) * 4;
;           const uint2 gz = *(const uint2*)(POST + (size_t)m * POST_W + QC_GATE + b * 1024 + n);
	v_mfma_f32_16x16x32_bf16 v[164:167], v[224:227], v[208:211], v[164:167]
	s_waitcnt lgkmcnt(2)
	v_mfma_f32_16x16x32_bf16 v[168:171], v[228:231], v[208:211], v[168:171]
	s_waitcnt lgkmcnt(1)
	v_mfma_f32_16x16x32_bf16 v[172:175], v[232:235], v[208:211], v[172:175]
	s_waitcnt lgkmcnt(0)
	v_mfma_f32_16x16x32_bf16 v[132:135], v[236:239], v[208:211], v[132:135]
	v_mfma_f32_16x16x32_bf16 v[160:163], v[224:227], v[212:215], v[160:163]
	v_mfma_f32_16x16x32_bf16 v[188:191], v[228:231], v[212:215], v[188:191]
	v_mfma_f32_16x16x32_bf16 v[192:195], v[232:235], v[212:215], v[192:195]
	v_mfma_f32_16x16x32_bf16 v[136:139], v[236:239], v[212:215], v[136:139]
	v_mfma_f32_16x16x32_bf16 v[196:199], v[224:227], v[216:219], v[196:199]
	v_mfma_f32_16x16x32_bf16 v[200:203], v[228:231], v[216:219], v[200:203]
	v_mfma_f32_16x16x32_bf16 v[204:207], v[232:235], v[216:219], v[204:207]
	v_mfma_f32_16x16x32_bf16 v[140:143], v[236:239], v[216:219], v[140:143]
	v_mfma_f32_16x16x32_bf16 v[148:151], v[224:227], v[220:223], v[148:151]
	v_mfma_f32_16x16x32_bf16 v[152:155], v[228:231], v[220:223], v[152:155]
	v_mfma_f32_16x16x32_bf16 v[156:159], v[232:235], v[220:223], v[156:159]
	v_mfma_f32_16x16x32_bf16 v[144:147], v[236:239], v[220:223], v[144:147]
	ds_read_b128 v[208:211], v129 offset:16384
	ds_read_b128 v[212:215], v129 offset:18432
	ds_read_b128 v[216:219], v129 offset:20480
	ds_read_b128 v[220:223], v129 offset:22528
	ds_read_b128 v[224:227], v130 offset:49152
	ds_read_b128 v[228:231], v130 offset:51200
	ds_read_b128 v[232:235], v130 offset:53248
	ds_read_b128 v[236:239], v130 offset:55296
	s_waitcnt vmcnt(7)
	ds_write_b128 v126, v[4:7]
	s_waitcnt vmcnt(6)
	ds_write_b128 v126, v[8:11] offset:32768
	s_waitcnt vmcnt(5)
	ds_write_b128 v126, v[12:15] offset:4096
	s_waitcnt vmcnt(4)
	ds_write_b128 v126, v[16:19] offset:36864
	s_waitcnt vmcnt(3)
	ds_write_b128 v126, v[20:23] offset:8192
	s_waitcnt vmcnt(2)
	ds_write_b128 v126, v[24:27] offset:40960
	s_waitcnt vmcnt(1)
	ds_write_b128 v126, v[28:31] offset:12288
	s_waitcnt vmcnt(0)
	ds_write_b128 v126, v[32:35] offset:45056
	s_waitcnt lgkmcnt(0)
	s_barrier
	global_load_dwordx4 v[4:7], v[36:37], off offset:896
	global_load_dwordx4 v[8:11], v[38:39], off offset:896
	global_load_dwordx4 v[12:15], v[40:41], off offset:896
	global_load_dwordx4 v[16:19], v[42:43], off offset:896
	global_load_dwordx4 v[20:23], v[44:45], off offset:896
	global_load_dwordx4 v[24:27], v[46:47], off offset:896
	global_load_dwordx4 v[28:31], v[48:49], off offset:896
	global_load_dwordx4 v[32:35], v[50:51], off offset:896
	v_mfma_f32_16x16x32_bf16 v[164:167], v[224:227], v[208:211], v[164:167]
	v_mfma_f32_16x16x32_bf16 v[168:171], v[228:231], v[208:211], v[168:171]
	v_mfma_f32_16x16x32_bf16 v[172:175], v[232:235], v[208:211], v[172:175]
	v_mfma_f32_16x16x32_bf16 v[132:135], v[236:239], v[208:211], v[132:135]
	v_mfma_f32_16x16x32_bf16 v[160:163], v[224:227], v[212:215], v[160:163]
	v_mfma_f32_16x16x32_bf16 v[188:191], v[228:231], v[212:215], v[188:191]
	v_mfma_f32_16x16x32_bf16 v[192:195], v[232:235], v[212:215], v[192:195]
	v_mfma_f32_16x16x32_bf16 v[136:139], v[236:239], v[212:215], v[136:139]
	v_mfma_f32_16x16x32_bf16 v[196:199], v[224:227], v[216:219], v[196:199]
	v_mfma_f32_16x16x32_bf16 v[200:203], v[228:231], v[216:219], v[200:203]
	v_mfma_f32_16x16x32_bf16 v[204:207], v[232:235], v[216:219], v[204:207]
	v_mfma_f32_16x16x32_bf16 v[140:143], v[236:239], v[216:219], v[140:143]
	v_mfma_f32_16x16x32_bf16 v[148:151], v[224:227], v[220:223], v[148:151]
	v_mfma_f32_16x16x32_bf16 v[152:155], v[228:231], v[220:223], v[152:155]
	v_mfma_f32_16x16x32_bf16 v[156:159], v[232:235], v[220:223], v[156:159]
	v_mfma_f32_16x16x32_bf16 v[144:147], v[236:239], v[220:223], v[144:147]
	global_load_dwordx2 v[224:225], v110, s[30:31] offset:3072
	global_load_dwordx2 v[226:227], v110, s[30:31] offset:3104
	global_load_dwordx2 v[228:229], v110, s[30:31] offset:3136
	global_load_dwordx2 v[230:231], v110, s[30:31] offset:3168
	global_load_dwordx2 v[232:233], v106, s[30:31] offset:3072
	global_load_dwordx2 v[234:235], v106, s[30:31] offset:3104
	global_load_dwordx2 v[236:237], v106, s[30:31] offset:3136
	global_load_dwordx2 v[238:239], v106, s[30:31] offset:3168
	ds_read_b128 v[36:39], v127
	ds_read_b128 v[40:43], v127 offset:2048
	ds_read_b128 v[44:47], v127 offset:4096
	ds_read_b128 v[48:51], v127 offset:6144
	ds_read_b128 v[208:211], v128 offset:32768
	ds_read_b128 v[212:215], v128 offset:34816
	ds_read_b128 v[216:219], v128 offset:36864
	ds_read_b128 v[220:223], v128 offset:38912
	s_waitcnt lgkmcnt(3)
	v_mfma_f32_16x16x32_bf16 v[164:167], v[208:211], v[36:39], v[164:167]
	s_waitcnt lgkmcnt(2)
	v_mfma_f32_16x16x32_bf16 v[168:171], v[212:215], v[36:39], v[168:171]
	s_waitcnt lgkmcnt(1)
	v_mfma_f32_16x16x32_bf16 v[172:175], v[216:219], v[36:39], v[172:175]
	s_waitcnt lgkmcnt(0)
	v_mfma_f32_16x16x32_bf16 v[36:39], v[220:223], v[36:39], v[132:135]
	v_mfma_f32_16x16x32_bf16 v[132:135], v[208:211], v[40:43], v[160:163]
	v_mfma_f32_16x16x32_bf16 v[160:163], v[212:215], v[40:43], v[188:191]
	v_mfma_f32_16x16x32_bf16 v[188:191], v[216:219], v[40:43], v[192:195]
	v_mfma_f32_16x16x32_bf16 v[40:43], v[220:223], v[40:43], v[136:139]
	v_mfma_f32_16x16x32_bf16 v[136:139], v[208:211], v[44:47], v[196:199]
	v_mfma_f32_16x16x32_bf16 v[192:195], v[212:215], v[44:47], v[200:203]
	v_mfma_f32_16x16x32_bf16 v[196:199], v[216:219], v[44:47], v[204:207]
	v_mfma_f32_16x16x32_bf16 v[44:47], v[220:223], v[44:47], v[140:143]
	v_mfma_f32_16x16x32_bf16 v[140:143], v[208:211], v[48:51], v[148:151]
	v_mfma_f32_16x16x32_bf16 v[148:151], v[212:215], v[48:51], v[152:155]
	v_mfma_f32_16x16x32_bf16 v[152:155], v[216:219], v[48:51], v[156:159]
	v_mfma_f32_16x16x32_bf16 v[48:51], v[220:223], v[48:51], v[144:147]
	s_nop 2
	ds_read_b128 v[144:147], v129
	ds_read_b128 v[156:159], v129 offset:2048
	ds_read_b128 v[200:203], v129 offset:4096
	ds_read_b128 v[204:207], v129 offset:6144
	ds_read_b128 v[208:211], v130 offset:32768
	ds_read_b128 v[212:215], v130 offset:34816
	ds_read_b128 v[216:219], v130 offset:36864
	ds_read_b128 v[220:223], v130 offset:38912
	s_waitcnt vmcnt(15)
	ds_write_b128 v126, v[4:7] offset:16384
	s_waitcnt vmcnt(14)
	ds_write_b128 v126, v[8:11] offset:49152
	s_waitcnt vmcnt(13)
	ds_write_b128 v126, v[12:15] offset:20480
	s_waitcnt vmcnt(12)
	ds_write_b128 v126, v[16:19] offset:53248
	s_waitcnt vmcnt(11)
	ds_write_b128 v126, v[20:23] offset:24576
	s_waitcnt vmcnt(10)
	ds_write_b128 v126, v[24:27] offset:57344
	s_waitcnt vmcnt(9)
	ds_write_b128 v126, v[28:31] offset:28672
	s_waitcnt vmcnt(8)
	ds_write_b128 v126, v[32:35] offset:61440
	s_waitcnt lgkmcnt(0)
	s_barrier
; __device__ __forceinline__ float bflo(unsigned u) { return __uint_as_float(u << 16); }
; __device__ __forceinline__ float bfhi(unsigned u) { return __uint_as_float(u & 0xffff0000u); }
; __device__ __forceinline__ float sigmoidf_(float x) { return frcp_(1.f + __expf(-x)); }
; __device__ __forceinline__ void mma_ktile(const bf16_t* cA, const bf16_t* cB, int fo0, int fo1, f32x4 (&acc)[4][4]) {
; #pragma unroll
;   for (int ks = 0; ks < 2; ++ks) {
;     const int fo = ks ? fo1 : fo0;
;     bf16x8 af[4], bfr[4];
; #pragma unroll
;     for (int i = 0; i < 4; ++i) af[i] = *(const bf16x8*)(cA + i * 16 * LDS_STRIDE + fo);
; #pragma unroll
;     for (int j = 0; j < 4; ++j) bfr[j] = *(const bf16x8*)(cB + j * 16 * LDS_STRIDE + fo);
; #pragma unroll
;     for (int i = 0; i < 4; ++i)
; #pragma unroll
;       for (int j = 0; j < 4; ++j)
;         acc[i][j] = __builtin_amdgcn_mfma_f32_16x16x32_bf16(bfr[j], af[i], acc[i][j], 0, 0, 0);
;   }
; }
; __device__ __forceinline__ void phase_gemm_merge(const Params& p, char* smem) {
;     ...
; #pragma unroll
;       for (int i = 0; i < 4; ++i) {
;         const int m = mt * 128 + wm * 64 + i * 16 + (lane & 15);
; #pragma unroll
;         for (int j = 0; j < 4; ++j) {
;           const int n = nt * 128 + wn * 64 + j * 16 + (lane >> 4) * 4;
;           const uint2 gz = *(const uint2*)(POST + (size_t)m * POST_W + QC_GATE + b * 1024 + n);
;           outv[i][j][0] += sigmoidf_(bflo(gz.x)) * acc[i][j][0];
;           outv[i][j][1] += sigmoidf_(bfhi(gz.x)) * acc[i][j][1];
;           outv[i][j][2] += sigmoidf_(bflo(gz.y)) * acc[i][j][2];
;           outv[i][j][3] += sigmoidf_(bfhi(gz.y)) * acc[i][j][3];
;         }
	ds_read_b128 v[4:7], v127 offset:16384
	ds_read_b128 v[8:11], v127 offset:18432
	ds_read_b128 v[12:15], v127 offset:20480
	ds_read_b128 v[16:19], v127 offset:22528
	ds_read_b128 v[20:23], v128 offset:49152
	ds_read_b128 v[24:27], v128 offset:51200
	ds_read_b128 v[28:31], v128 offset:53248
	ds_read_b128 v[32:35], v128 offset:55296
	v_mfma_f32_16x16x32_bf16 v[164:167], v[208:211], v[144:147], v[164:167]
	v_mfma_f32_16x16x32_bf16 v[168:171], v[212:215], v[144:147], v[168:171]
	v_mfma_f32_16x16x32_bf16 v[172:175], v[216:219], v[144:147], v[172:175]
	v_mfma_f32_16x16x32_bf16 v[36:39], v[220:223], v[144:147], v[36:39]
	v_mfma_f32_16x16x32_bf16 v[132:135], v[208:211], v[156:159], v[132:135]
	v_mfma_f32_16x16x32_bf16 v[144:147], v[212:215], v[156:159], v[160:163]
	v_mfma_f32_16x16x32_bf16 v[160:163], v[216:219], v[156:159], v[188:191]
	v_mfma_f32_16x16x32_bf16 v[136:139], v[208:211], v[200:203], v[136:139]
	v_mfma_f32_16x16x32_bf16 v[188:191], v[216:219], v[200:203], v[196:199]
	v_mfma_f32_16x16x32_bf16 v[140:143], v[208:211], v[204:207], v[140:143]
	v_mfma_f32_16x16x32_bf16 v[148:151], v[212:215], v[204:207], v[148:151]
	v_mfma_f32_16x16x32_bf16 v[152:155], v[216:219], v[204:207], v[152:155]
	v_mfma_f32_16x16x32_bf16 v[48:51], v[220:223], v[204:207], v[48:51]
	v_mfma_f32_16x16x32_bf16 v[40:43], v[220:223], v[156:159], v[40:43]
	v_mfma_f32_16x16x32_bf16 v[156:159], v[212:215], v[200:203], v[192:195]
	v_mfma_f32_16x16x32_bf16 v[44:47], v[220:223], v[200:203], v[44:47]
	s_waitcnt lgkmcnt(3)
	v_mfma_f32_16x16x32_bf16 v[164:167], v[20:23], v[4:7], v[164:167]
	s_waitcnt lgkmcnt(2)
	v_mfma_f32_16x16x32_bf16 v[168:171], v[24:27], v[4:7], v[168:171]
	s_waitcnt lgkmcnt(1)
	v_mfma_f32_16x16x32_bf16 v[172:175], v[28:31], v[4:7], v[172:175]
	s_waitcnt lgkmcnt(0)
	v_mfma_f32_16x16x32_bf16 v[4:7], v[32:35], v[4:7], v[36:39]
	v_mfma_f32_16x16x32_bf16 v[36:39], v[20:23], v[8:11], v[132:135]
	v_mfma_f32_16x16x32_bf16 v[132:135], v[24:27], v[8:11], v[144:147]
	v_mfma_f32_16x16x32_bf16 v[144:147], v[28:31], v[8:11], v[160:163]
	v_mfma_f32_16x16x32_bf16 v[136:139], v[20:23], v[12:15], v[136:139]
	v_mfma_f32_16x16x32_bf16 v[160:163], v[28:31], v[12:15], v[188:191]
	v_mfma_f32_16x16x32_bf16 v[140:143], v[20:23], v[16:19], v[140:143]
	v_mfma_f32_16x16x32_bf16 v[148:151], v[24:27], v[16:19], v[148:151]
	v_mfma_f32_16x16x32_bf16 v[152:155], v[28:31], v[16:19], v[152:155]
	v_mfma_f32_16x16x32_bf16 v[188:191], v[32:35], v[16:19], v[48:51]
	ds_read_b128 v[16:19], v129 offset:16384
	ds_read_b128 v[20:23], v129 offset:18432
	ds_read_b128 v[192:195], v129 offset:20480
	ds_read_b128 v[126:129], v129 offset:22528
	ds_read_b128 v[196:199], v130 offset:49152
	ds_read_b128 v[200:203], v130 offset:51200
	ds_read_b128 v[204:207], v130 offset:53248
	ds_read_b128 v[208:211], v130 offset:55296
	s_waitcnt lgkmcnt(0)
	s_barrier
	v_mfma_f32_16x16x32_bf16 v[8:11], v[32:35], v[8:11], v[40:43]
	v_mfma_f32_16x16x32_bf16 v[156:159], v[24:27], v[12:15], v[156:159]
	v_mfma_f32_16x16x32_bf16 v[12:15], v[32:35], v[12:15], v[44:47]
	v_mfma_f32_16x16x32_bf16 v[164:167], v[196:199], v[16:19], v[164:167]
	v_mfma_f32_16x16x32_bf16 v[168:171], v[200:203], v[16:19], v[168:171]
	v_mfma_f32_16x16x32_bf16 v[172:175], v[204:207], v[16:19], v[172:175]
	v_mfma_f32_16x16x32_bf16 v[212:215], v[208:211], v[16:19], v[4:7]
	v_mfma_f32_16x16x32_bf16 v[48:51], v[196:199], v[20:23], v[36:39]
	v_mfma_f32_16x16x32_bf16 v[44:47], v[200:203], v[20:23], v[132:135]
	v_mfma_f32_16x16x32_bf16 v[40:43], v[204:207], v[20:23], v[144:147]
	s_nop 1
	v_mov_b32_e32 v133, v166
	v_mov_b32_e32 v166, v165
	v_mov_b32_e32 v132, v164
	v_mfma_f32_16x16x32_bf16 v[36:39], v[208:211], v[20:23], v[8:11]
	v_mfma_f32_16x16x32_bf16 v[20:23], v[208:211], v[192:195], v[12:15]
	v_mfma_f32_16x16x32_bf16 v[16:19], v[196:199], v[126:129], v[140:143]
	v_mfma_f32_16x16x32_bf16 v[12:15], v[200:203], v[126:129], v[148:151]
	v_mfma_f32_16x16x32_bf16 v[8:11], v[204:207], v[126:129], v[152:155]
	v_mfma_f32_16x16x32_bf16 v[4:7], v[208:211], v[126:129], v[188:191]
	v_lshl_add_u64 v[126:127], s[10:11], 0, v[110:111]
	v_add_co_u32_e32 v126, vcc, s59, v126
	v_mfma_f32_16x16x32_bf16 v[32:35], v[196:199], v[192:195], v[136:139]
	s_nop 0
	v_addc_co_u32_e32 v127, vcc, 0, v127, vcc
	s_waitcnt vmcnt(7)
	v_mov_b32_e32 v128, v224
	v_mov_b32_e32 v129, v225
	global_load_dwordx2 v[224:225], v104, s[30:31] offset:3072
	v_mfma_f32_16x16x32_bf16 v[28:31], v[200:203], v[192:195], v[156:159]
	v_lshl_add_u64 v[110:111], v[110:111], 0, s[38:39]
	s_nop 0
	v_lshlrev_b32_e32 v130, 16, v128
	v_and_b32_e32 v128, 0xffff0000, v128
	v_lshlrev_b32_e32 v131, 16, v129
	v_and_b32_e32 v129, 0xffff0000, v129
	v_mul_f32_e32 v128, 0xbfb8aa3b, v128
	v_mul_f32_e32 v129, 0xbfb8aa3b, v129
	v_exp_f32_e32 v128, v128
	v_exp_f32_e32 v129, v129
	v_mul_f32_e32 v130, 0xbfb8aa3b, v130
	v_mul_f32_e32 v131, 0xbfb8aa3b, v131
	v_add_f32_e32 v128, 1.0, v128
	v_add_f32_e32 v129, 1.0, v129
	v_rcp_f32_e32 v128, v128
	v_rcp_f32_e32 v129, v129
	v_exp_f32_e32 v130, v130
	v_exp_f32_e32 v131, v131
	v_mfma_f32_16x16x32_bf16 v[24:27], v[204:207], v[192:195], v[160:163]
	v_fma_f32 v118, v166, v128, v118
	v_fma_f32 v119, v167, v129, v119
	s_waitcnt vmcnt(7)
; __device__ __forceinline__ float bflo(unsigned u) { return __uint_as_float(u << 16); }
; __device__ __forceinline__ float bfhi(unsigned u) { return __uint_as_float(u & 0xffff0000u); }
; __device__ __forceinline__ float sigmoidf_(float x) { return frcp_(1.f + __expf(-x)); }
; __device__ __forceinline__ void phase_gemm_merge(const Params& p, char* smem) {
;     ...
; #pragma unroll
;       for (int i = 0; i < 4; ++i) {
;         const int m = mt * 128 + wm * 64 + i * 16 + (lane & 15);
; #pragma unroll
;         for (int j = 0; j < 4; ++j) {
;           const int n = nt * 128 + wn * 64 + j * 16 + (lane >> 4) * 4;
;           const uint2 gz = *(const uint2*)(POST + (size_t)m * POST_W + QC_GATE + b * 1024 + n);
;           outv[i][j][0] += sigmoidf_(bflo(gz.x)) * acc[i][j][0];
;           outv[i][j][1] += sigmoidf_(bfhi(gz.x)) * acc[i][j][1];
;           outv[i][j][2] += sigmoidf_(bflo(gz.y)) * acc[i][j][2];
;           outv[i][j][3] += sigmoidf_(bfhi(gz.y)) * acc[i][j][3];
;         }
;       }
	v_mov_b32_e32 v128, v226
	v_mov_b32_e32 v129, v227
	global_load_dwordx2 v[226:227], v104, s[30:31] offset:3104
	v_add_f32_e32 v130, 1.0, v130
	v_add_f32_e32 v131, 1.0, v131
	v_rcp_f32_e32 v130, v130
	v_rcp_f32_e32 v131, v131
	s_nop 0
	v_pk_fma_f32 v[120:121], v[132:133], v[130:131], v[120:121]
	v_mov_b32_e32 v133, v170
	v_mov_b32_e32 v170, v169
	v_mov_b32_e32 v132, v168
	s_nop 0
	v_lshlrev_b32_e32 v130, 16, v128
	v_and_b32_e32 v128, 0xffff0000, v128
	v_lshlrev_b32_e32 v131, 16, v129
	v_and_b32_e32 v129, 0xffff0000, v129
	v_mul_f32_e32 v128, 0xbfb8aa3b, v128
	v_mul_f32_e32 v129, 0xbfb8aa3b, v129
	v_exp_f32_e32 v128, v128
	v_exp_f32_e32 v129, v129
	v_mul_f32_e32 v130, 0xbfb8aa3b, v130
	v_mul_f32_e32 v131, 0xbfb8aa3b, v131
	v_add_f32_e32 v128, 1.0, v128
	v_add_f32_e32 v129, 1.0, v129
	v_rcp_f32_e32 v128, v128
	v_rcp_f32_e32 v129, v129
	v_exp_f32_e32 v130, v130
	v_exp_f32_e32 v131, v131
	v_pk_fma_f32 v[114:115], v[170:171], v[128:129], v[114:115]
	s_waitcnt vmcnt(7)
	v_mov_b32_e32 v128, v228
	v_mov_b32_e32 v129, v229
	global_load_dwordx2 v[228:229], v104, s[30:31] offset:3136
	v_add_f32_e32 v130, 1.0, v130
	s_waitcnt vmcnt(7)
	v_mov_b32_e32 v126, v230
	v_mov_b32_e32 v127, v231
	global_load_dwordx2 v[230:231], v104, s[30:31] offset:3168
	v_add_f32_e32 v131, 1.0, v131
	v_rcp_f32_e32 v130, v130
	v_rcp_f32_e32 v131, v131
	s_nop 0
	v_pk_fma_f32 v[116:117], v[132:133], v[130:131], v[116:117]
	v_mov_b32_e32 v133, v174
	v_mov_b32_e32 v174, v173
	v_mov_b32_e32 v132, v172
	s_nop 0
	v_lshlrev_b32_e32 v130, 16, v128
	v_and_b32_e32 v128, 0xffff0000, v128
	v_lshlrev_b32_e32 v131, 16, v129
	v_and_b32_e32 v129, 0xffff0000, v129
	v_mul_f32_e32 v128, 0xbfb8aa3b, v128
	v_mul_f32_e32 v129, 0xbfb8aa3b, v129
	v_exp_f32_e32 v128, v128
	v_exp_f32_e32 v129, v129
	v_mul_f32_e32 v130, 0xbfb8aa3b, v130
	v_mul_f32_e32 v131, 0xbfb8aa3b, v131
	v_add_f32_e32 v128, 1.0, v128
	v_add_f32_e32 v129, 1.0, v129
	v_rcp_f32_e32 v128, v128
	v_rcp_f32_e32 v129, v129
	v_exp_f32_e32 v130, v130
	v_exp_f32_e32 v131, v131
	v_pk_fma_f32 v[108:109], v[174:175], v[128:129], v[108:109]
	s_nop 0
	v_lshlrev_b32_e32 v128, 16, v126
	v_and_b32_e32 v126, 0xffff0000, v126
	v_lshlrev_b32_e32 v129, 16, v127
	v_and_b32_e32 v127, 0xffff0000, v127
	v_mul_f32_e32 v126, 0xbfb8aa3b, v126
	v_mul_f32_e32 v127, 0xbfb8aa3b, v127
	v_exp_f32_e32 v126, v126
	v_exp_f32_e32 v127, v127
	v_mul_f32_e32 v128, 0xbfb8aa3b, v128
	v_mul_f32_e32 v129, 0xbfb8aa3b, v129
	v_add_f32_e32 v130, 1.0, v130
	v_add_f32_e32 v131, 1.0, v131
	v_exp_f32_e32 v128, v128
	v_exp_f32_e32 v129, v129
	v_rcp_f32_e32 v130, v130
	v_rcp_f32_e32 v131, v131
	v_add_f32_e32 v126, 1.0, v126
	v_add_f32_e32 v127, 1.0, v127
	v_rcp_f32_e32 v126, v126
	v_rcp_f32_e32 v127, v127
	v_add_f32_e32 v128, 1.0, v128
	v_add_f32_e32 v129, 1.0, v129
	v_pk_fma_f32 v[112:113], v[132:133], v[130:131], v[112:113]
	v_rcp_f32_e32 v128, v128
	v_rcp_f32_e32 v129, v129
	v_mov_b32_e32 v131, v214
	v_mov_b32_e32 v214, v213
	v_pk_fma_f32 v[98:99], v[214:215], v[126:127], v[98:99]
	v_lshl_add_u64 v[126:127], s[10:11], 0, v[106:107]
	v_add_co_u32_e32 v126, vcc, s59, v126
	v_mov_b32_e32 v130, v212
	s_nop 0
	v_addc_co_u32_e32 v127, vcc, 0, v127, vcc
	v_pk_fma_f32 v[100:101], v[130:131], v[128:129], v[100:101]
	s_waitcnt vmcnt(7)
	v_mov_b32_e32 v128, v232
	v_mov_b32_e32 v129, v233
	global_load_dwordx2 v[232:233], v102, s[30:31] offset:3072
	v_mov_b32_e32 v132, v48
	v_mov_b32_e32 v133, v50
	v_mov_b32_e32 v50, v49
	s_waitcnt vmcnt(7)
	v_mov_b32_e32 v48, v234
	v_mov_b32_e32 v49, v235
	global_load_dwordx2 v[234:235], v102, s[30:31] offset:3104
	v_lshl_add_u64 v[106:107], v[106:107], 0, s[38:39]
	s_nop 0
	v_lshlrev_b32_e32 v130, 16, v128
	v_and_b32_e32 v128, 0xffff0000, v128
	v_lshlrev_b32_e32 v131, 16, v129
	v_and_b32_e32 v129, 0xffff0000, v129
	v_mul_f32_e32 v128, 0xbfb8aa3b, v128
	v_mul_f32_e32 v129, 0xbfb8aa3b, v129
	v_exp_f32_e32 v128, v128
	v_exp_f32_e32 v129, v129
	v_mul_f32_e32 v130, 0xbfb8aa3b, v130
	v_mul_f32_e32 v131, 0xbfb8aa3b, v131
	v_add_f32_e32 v128, 1.0, v128
	v_add_f32_e32 v129, 1.0, v129
	v_rcp_f32_e32 v128, v128
	v_rcp_f32_e32 v129, v129
	v_exp_f32_e32 v130, v130
	v_exp_f32_e32 v131, v131
	v_pk_fma_f32 v[94:95], v[50:51], v[128:129], v[94:95]
	s_nop 0
	v_lshlrev_b32_e32 v50, 16, v48
	v_and_b32_e32 v48, 0xffff0000, v48
	v_lshlrev_b32_e32 v51, 16, v49
	v_and_b32_e32 v49, 0xffff0000, v49
	v_mov_b32_e32 v128, v44
	v_mov_b32_e32 v129, v46
	v_mov_b32_e32 v46, v45
	s_waitcnt vmcnt(7)
	v_mov_b32_e32 v44, v236
	v_mov_b32_e32 v45, v237
	global_load_dwordx2 v[236:237], v102, s[30:31] offset:3136
	v_mul_f32_e32 v48, 0xbfb8aa3b, v48
	v_mul_f32_e32 v49, 0xbfb8aa3b, v49
	v_exp_f32_e32 v48, v48
	v_exp_f32_e32 v49, v49
	v_mul_f32_e32 v50, 0xbfb8aa3b, v50
	v_mul_f32_e32 v51, 0xbfb8aa3b, v51
	v_add_f32_e32 v48, 1.0, v48
	v_add_f32_e32 v49, 1.0, v49
	v_rcp_f32_e32 v48, v48
	v_rcp_f32_e32 v49, v49
	v_exp_f32_e32 v50, v50
	v_exp_f32_e32 v51, v51
	v_add_f32_e32 v130, 1.0, v130
	v_pk_fma_f32 v[90:91], v[46:47], v[48:49], v[90:91]
	v_mov_b32_e32 v48, v40
	v_mov_b32_e32 v49, v42
	v_mov_b32_e32 v42, v41
	s_waitcnt vmcnt(7)
; __device__ __forceinline__ float bflo(unsigned u) { return __uint_as_float(u << 16); }
; __device__ __forceinline__ float bfhi(unsigned u) { return __uint_as_float(u & 0xffff0000u); }
; __device__ __forceinline__ float sigmoidf_(float x) { return frcp_(1.f + __expf(-x)); }
; __device__ __forceinline__ void phase_gemm_merge(const Params& p, char* smem) {
;     ...
; #pragma unroll
;       for (int i = 0; i < 4; ++i) {
;         const int m = mt * 128 + wm * 64 + i * 16 + (lane & 15);
; #pragma unroll
;         for (int j = 0; j < 4; ++j) {
;           const int n = nt * 128 + wn * 64 + j * 16 + (lane >> 4) * 4;
;           const uint2 gz = *(const uint2*)(POST + (size_t)m * POST_W + QC_GATE + b * 1024 + n);
;           outv[i][j][0] += sigmoidf_(bflo(gz.x)) * acc[i][j][0];
;           outv[i][j][1] += sigmoidf_(bfhi(gz.x)) * acc[i][j][1];
;           outv[i][j][2] += sigmoidf_(bflo(gz.y)) * acc[i][j][2];
;           outv[i][j][3] += sigmoidf_(bfhi(gz.y)) * acc[i][j][3];
;         }
;       }
	v_mov_b32_e32 v40, v238
	v_mov_b32_e32 v41, v239
	global_load_dwordx2 v[238:239], v102, s[30:31] offset:3168
	v_add_f32_e32 v131, 1.0, v131
	v_add_f32_e32 v50, 1.0, v50
	v_add_f32_e32 v51, 1.0, v51
	v_rcp_f32_e32 v130, v130
	v_rcp_f32_e32 v131, v131
	v_rcp_f32_e32 v50, v50
	v_rcp_f32_e32 v51, v51
	v_pk_fma_f32 v[96:97], v[132:133], v[130:131], v[96:97]
	v_pk_fma_f32 v[92:93], v[128:129], v[50:51], v[92:93]
	s_nop 0
	v_lshlrev_b32_e32 v46, 16, v44
	v_and_b32_e32 v44, 0xffff0000, v44
	v_lshlrev_b32_e32 v47, 16, v45
	v_and_b32_e32 v45, 0xffff0000, v45
	v_mul_f32_e32 v44, 0xbfb8aa3b, v44
	v_mul_f32_e32 v45, 0xbfb8aa3b, v45
	v_exp_f32_e32 v44, v44
	v_exp_f32_e32 v45, v45
	v_mul_f32_e32 v46, 0xbfb8aa3b, v46
	v_mul_f32_e32 v47, 0xbfb8aa3b, v47
	v_add_f32_e32 v44, 1.0, v44
	v_add_f32_e32 v45, 1.0, v45
	v_rcp_f32_e32 v44, v44
	v_rcp_f32_e32 v45, v45
	v_exp_f32_e32 v46, v46
	v_exp_f32_e32 v47, v47
	v_pk_fma_f32 v[86:87], v[42:43], v[44:45], v[86:87]
	s_nop 0
	v_lshlrev_b32_e32 v42, 16, v40
	v_and_b32_e32 v40, 0xffff0000, v40
	v_lshlrev_b32_e32 v43, 16, v41
	v_and_b32_e32 v41, 0xffff0000, v41
	v_mul_f32_e32 v40, 0xbfb8aa3b, v40
	v_mul_f32_e32 v41, 0xbfb8aa3b, v41
	v_exp_f32_e32 v40, v40
	v_exp_f32_e32 v41, v41
	v_mov_b32_e32 v44, v36
	v_mov_b32_e32 v45, v38
	v_add_f32_e32 v40, 1.0, v40
	v_add_f32_e32 v41, 1.0, v41
	v_rcp_f32_e32 v40, v40
	v_rcp_f32_e32 v41, v41
	v_mov_b32_e32 v38, v37
	v_lshl_add_u64 v[36:37], s[10:11], 0, v[104:105]
	v_add_co_u32_e32 v36, vcc, s59, v36
	v_pk_fma_f32 v[82:83], v[38:39], v[40:41], v[82:83]
	s_nop 0
	v_addc_co_u32_e32 v37, vcc, 0, v37, vcc
	s_waitcnt vmcnt(7)
	v_mov_b32_e32 v38, v224
	v_mov_b32_e32 v39, v225
	v_mul_f32_e32 v42, 0xbfb8aa3b, v42
	v_mul_f32_e32 v43, 0xbfb8aa3b, v43
	v_exp_f32_e32 v42, v42
	v_exp_f32_e32 v43, v43
	v_add_f32_e32 v46, 1.0, v46
	v_add_f32_e32 v47, 1.0, v47
	v_add_f32_e32 v42, 1.0, v42
	v_add_f32_e32 v43, 1.0, v43
	v_rcp_f32_e32 v42, v42
	v_rcp_f32_e32 v43, v43
	v_rcp_f32_e32 v46, v46
	v_rcp_f32_e32 v47, v47
	v_lshl_add_u64 v[104:105], v[104:105], 0, s[38:39]
	v_pk_fma_f32 v[84:85], v[44:45], v[42:43], v[84:85]
	v_mov_b32_e32 v42, v32
	v_mov_b32_e32 v43, v34
	v_mov_b32_e32 v34, v33
	s_waitcnt vmcnt(6)
	v_mov_b32_e32 v32, v226
	v_mov_b32_e32 v33, v227
	v_pk_fma_f32 v[88:89], v[48:49], v[46:47], v[88:89]
	s_nop 0
	v_lshlrev_b32_e32 v40, 16, v38
	v_and_b32_e32 v38, 0xffff0000, v38
	v_lshlrev_b32_e32 v41, 16, v39
	v_and_b32_e32 v39, 0xffff0000, v39
	v_mul_f32_e32 v38, 0xbfb8aa3b, v38
	v_mul_f32_e32 v39, 0xbfb8aa3b, v39
	v_exp_f32_e32 v38, v38
	v_exp_f32_e32 v39, v39
	v_mul_f32_e32 v40, 0xbfb8aa3b, v40
	v_mul_f32_e32 v41, 0xbfb8aa3b, v41
	v_add_f32_e32 v38, 1.0, v38
	v_add_f32_e32 v39, 1.0, v39
	v_rcp_f32_e32 v38, v38
	v_rcp_f32_e32 v39, v39
	v_exp_f32_e32 v40, v40
	v_exp_f32_e32 v41, v41
	v_pk_fma_f32 v[78:79], v[34:35], v[38:39], v[78:79]
	s_nop 0
	v_lshlrev_b32_e32 v34, 16, v32
	v_and_b32_e32 v32, 0xffff0000, v32
	v_lshlrev_b32_e32 v35, 16, v33
	v_and_b32_e32 v33, 0xffff0000, v33
	v_mov_b32_e32 v38, v28
	v_mov_b32_e32 v39, v30
	v_mov_b32_e32 v30, v29
	s_waitcnt vmcnt(5)
	v_mov_b32_e32 v28, v228
	v_mov_b32_e32 v29, v229
	v_mul_f32_e32 v32, 0xbfb8aa3b, v32
	v_mul_f32_e32 v33, 0xbfb8aa3b, v33
	v_exp_f32_e32 v32, v32
	v_exp_f32_e32 v33, v33
	v_mul_f32_e32 v34, 0xbfb8aa3b, v34
	v_mul_f32_e32 v35, 0xbfb8aa3b, v35
	v_add_f32_e32 v32, 1.0, v32
	v_add_f32_e32 v33, 1.0, v33
	v_rcp_f32_e32 v32, v32
	v_rcp_f32_e32 v33, v33
	v_exp_f32_e32 v34, v34
	v_exp_f32_e32 v35, v35
	v_add_f32_e32 v40, 1.0, v40
	v_pk_fma_f32 v[74:75], v[30:31], v[32:33], v[74:75]
	v_mov_b32_e32 v32, v24
	v_mov_b32_e32 v33, v26
	v_mov_b32_e32 v26, v25
	s_waitcnt vmcnt(4)
	v_mov_b32_e32 v24, v230
	v_mov_b32_e32 v25, v231
	v_add_f32_e32 v41, 1.0, v41
	v_add_f32_e32 v34, 1.0, v34
	v_add_f32_e32 v35, 1.0, v35
	v_rcp_f32_e32 v40, v40
	v_rcp_f32_e32 v41, v41
	v_rcp_f32_e32 v34, v34
	v_rcp_f32_e32 v35, v35
	v_pk_fma_f32 v[80:81], v[42:43], v[40:41], v[80:81]
	v_pk_fma_f32 v[76:77], v[38:39], v[34:35], v[76:77]
	s_nop 0
	v_lshlrev_b32_e32 v30, 16, v28
	v_and_b32_e32 v28, 0xffff0000, v28
	v_lshlrev_b32_e32 v31, 16, v29
	v_and_b32_e32 v29, 0xffff0000, v29
	v_mul_f32_e32 v28, 0xbfb8aa3b, v28
	v_mul_f32_e32 v29, 0xbfb8aa3b, v29
	v_exp_f32_e32 v28, v28
	v_exp_f32_e32 v29, v29
	v_mul_f32_e32 v30, 0xbfb8aa3b, v30
	v_mul_f32_e32 v31, 0xbfb8aa3b, v31
	v_add_f32_e32 v28, 1.0, v28
	v_add_f32_e32 v29, 1.0, v29
	v_rcp_f32_e32 v28, v28
	v_rcp_f32_e32 v29, v29
	v_exp_f32_e32 v30, v30
	v_exp_f32_e32 v31, v31
	v_pk_fma_f32 v[70:71], v[26:27], v[28:29], v[70:71]
	s_nop 0
	v_lshlrev_b32_e32 v26, 16, v24
	v_and_b32_e32 v24, 0xffff0000, v24
	v_lshlrev_b32_e32 v27, 16, v25
	v_and_b32_e32 v25, 0xffff0000, v25
	v_mul_f32_e32 v24, 0xbfb8aa3b, v24
	v_mul_f32_e32 v25, 0xbfb8aa3b, v25
	v_exp_f32_e32 v24, v24
	v_exp_f32_e32 v25, v25
	v_mov_b32_e32 v28, v20
	v_mov_b32_e32 v29, v22
	v_add_f32_e32 v24, 1.0, v24
	v_add_f32_e32 v25, 1.0, v25
	v_rcp_f32_e32 v24, v24
	v_rcp_f32_e32 v25, v25
	v_mov_b32_e32 v22, v21
	v_lshl_add_u64 v[20:21], s[10:11], 0, v[102:103]
	v_add_co_u32_e32 v20, vcc, s59, v20
	v_pk_fma_f32 v[66:67], v[22:23], v[24:25], v[66:67]
	s_nop 0
	v_addc_co_u32_e32 v21, vcc, 0, v21, vcc
	s_waitcnt vmcnt(3)
	v_mov_b32_e32 v22, v232
	v_mov_b32_e32 v23, v233
	v_mul_f32_e32 v26, 0xbfb8aa3b, v26
	v_mul_f32_e32 v27, 0xbfb8aa3b, v27
	v_exp_f32_e32 v26, v26
	v_exp_f32_e32 v27, v27
	v_add_f32_e32 v30, 1.0, v30
	v_add_f32_e32 v31, 1.0, v31
	v_add_f32_e32 v26, 1.0, v26
	v_add_f32_e32 v27, 1.0, v27
	v_rcp_f32_e32 v26, v26
	v_rcp_f32_e32 v27, v27
	v_rcp_f32_e32 v30, v30
	v_rcp_f32_e32 v31, v31
	v_lshl_add_u64 v[102:103], v[102:103], 0, s[38:39]
	v_pk_fma_f32 v[68:69], v[28:29], v[26:27], v[68:69]
	v_mov_b32_e32 v26, v16
	v_mov_b32_e32 v27, v18
	v_mov_b32_e32 v18, v17
	s_waitcnt vmcnt(2)
; __device__ __forceinline__ unsigned pack2(float a, float b) { return (unsigned)f2bf(a) | ((unsigned)f2bf(b) << 16); }
; __device__ __forceinline__ float bflo(unsigned u) { return __uint_as_float(u << 16); }
; __device__ __forceinline__ float bfhi(unsigned u) { return __uint_as_float(u & 0xffff0000u); }
; __device__ __forceinline__ float sigmoidf_(float x) { return frcp_(1.f + __expf(-x)); }
; __device__ __forceinline__ void phase_gemm_merge(const Params& p, char* smem) {
;     ...
; #pragma unroll
;       for (int i = 0; i < 4; ++i) {
;         const int m = mt * 128 + wm * 64 + i * 16 + (lane & 15);
; #pragma unroll
;         for (int j = 0; j < 4; ++j) {
;           const int n = nt * 128 + wn * 64 + j * 16 + (lane >> 4) * 4;
;           const uint2 gz = *(const uint2*)(POST + (size_t)m * POST_W + QC_GATE + b * 1024 + n);
;           outv[i][j][0] += sigmoidf_(bflo(gz.x)) * acc[i][j][0];
;           outv[i][j][1] += sigmoidf_(bfhi(gz.x)) * acc[i][j][1];
;           outv[i][j][2] += sigmoidf_(bflo(gz.y)) * acc[i][j][2];
;           outv[i][j][3] += sigmoidf_(bfhi(gz.y)) * acc[i][j][3];
;         }
;       }
;     }
; #pragma unroll
;     for (int i = 0; i < 4; ++i) {
;       const int m = mt * 128 + wm * 64 + i * 16 + (lane & 15);
; #pragma unroll
;       for (int j = 0; j < 4; ++j) {
;         const int n = nt * 128 + wn * 64 + j * 16 + (lane >> 4) * 4;
;         uint2 o;
;         o.x = pack2(outv[i][j][0], outv[i][j][1]);
;         o.y = pack2(outv[i][j][2], outv[i][j][3]);
;         *(uint2*)(MG + (size_t)m * 1024 + n) = o;
;       }
	v_mov_b32_e32 v16, v234
	v_mov_b32_e32 v17, v235
	v_pk_fma_f32 v[72:73], v[32:33], v[30:31], v[72:73]
	s_nop 0
	v_lshlrev_b32_e32 v24, 16, v22
	v_and_b32_e32 v22, 0xffff0000, v22
	v_lshlrev_b32_e32 v25, 16, v23
	v_and_b32_e32 v23, 0xffff0000, v23
	v_mul_f32_e32 v22, 0xbfb8aa3b, v22
	v_mul_f32_e32 v23, 0xbfb8aa3b, v23
	v_exp_f32_e32 v22, v22
	v_exp_f32_e32 v23, v23
	v_mul_f32_e32 v24, 0xbfb8aa3b, v24
	v_mul_f32_e32 v25, 0xbfb8aa3b, v25
	v_add_f32_e32 v22, 1.0, v22
	v_add_f32_e32 v23, 1.0, v23
	v_rcp_f32_e32 v22, v22
	v_rcp_f32_e32 v23, v23
	v_exp_f32_e32 v24, v24
	v_exp_f32_e32 v25, v25
	v_pk_fma_f32 v[62:63], v[18:19], v[22:23], v[62:63]
	s_nop 0
	v_lshlrev_b32_e32 v18, 16, v16
	v_and_b32_e32 v16, 0xffff0000, v16
	v_lshlrev_b32_e32 v19, 16, v17
	v_and_b32_e32 v17, 0xffff0000, v17
	v_mov_b32_e32 v22, v12
	v_mov_b32_e32 v23, v14
	v_mov_b32_e32 v14, v13
	s_waitcnt vmcnt(1)
	v_mov_b32_e32 v12, v236
	v_mov_b32_e32 v13, v237
	v_mul_f32_e32 v16, 0xbfb8aa3b, v16
	v_mul_f32_e32 v17, 0xbfb8aa3b, v17
	v_exp_f32_e32 v16, v16
	v_exp_f32_e32 v17, v17
	v_mul_f32_e32 v18, 0xbfb8aa3b, v18
	v_mul_f32_e32 v19, 0xbfb8aa3b, v19
	v_add_f32_e32 v16, 1.0, v16
	v_add_f32_e32 v17, 1.0, v17
	v_rcp_f32_e32 v16, v16
	v_rcp_f32_e32 v17, v17
	v_exp_f32_e32 v18, v18
	v_exp_f32_e32 v19, v19
	v_add_f32_e32 v24, 1.0, v24
	v_pk_fma_f32 v[58:59], v[14:15], v[16:17], v[58:59]
	v_mov_b32_e32 v16, v8
	v_mov_b32_e32 v17, v10
	v_mov_b32_e32 v10, v9
	s_waitcnt vmcnt(0)
	v_mov_b32_e32 v8, v238
	v_mov_b32_e32 v9, v239
	v_add_f32_e32 v25, 1.0, v25
	v_add_f32_e32 v18, 1.0, v18
	v_add_f32_e32 v19, 1.0, v19
	v_rcp_f32_e32 v24, v24
	v_rcp_f32_e32 v25, v25
	v_rcp_f32_e32 v18, v18
	v_rcp_f32_e32 v19, v19
	v_pk_fma_f32 v[64:65], v[26:27], v[24:25], v[64:65]
	v_pk_fma_f32 v[60:61], v[22:23], v[18:19], v[60:61]
	s_nop 0
	v_lshlrev_b32_e32 v14, 16, v12
	v_and_b32_e32 v12, 0xffff0000, v12
	v_lshlrev_b32_e32 v15, 16, v13
	v_and_b32_e32 v13, 0xffff0000, v13
	v_mul_f32_e32 v12, 0xbfb8aa3b, v12
	v_mul_f32_e32 v13, 0xbfb8aa3b, v13
	v_exp_f32_e32 v12, v12
	v_exp_f32_e32 v13, v13
	v_mul_f32_e32 v14, 0xbfb8aa3b, v14
	v_mul_f32_e32 v15, 0xbfb8aa3b, v15
	v_add_f32_e32 v12, 1.0, v12
	v_add_f32_e32 v13, 1.0, v13
	v_rcp_f32_e32 v12, v12
	v_rcp_f32_e32 v13, v13
	v_exp_f32_e32 v14, v14
	v_exp_f32_e32 v15, v15
	v_pk_fma_f32 v[54:55], v[10:11], v[12:13], v[54:55]
	s_nop 0
	v_lshlrev_b32_e32 v10, 16, v8
	v_and_b32_e32 v8, 0xffff0000, v8
	v_lshlrev_b32_e32 v11, 16, v9
	v_and_b32_e32 v9, 0xffff0000, v9
	v_mul_f32_e32 v10, 0xbfb8aa3b, v10
	v_mul_f32_e32 v8, 0xbfb8aa3b, v8
	v_mul_f32_e32 v11, 0xbfb8aa3b, v11
	v_mul_f32_e32 v9, 0xbfb8aa3b, v9
	v_exp_f32_e32 v10, v10
	v_exp_f32_e32 v8, v8
	v_exp_f32_e32 v11, v11
	v_exp_f32_e32 v9, v9
	v_add_f32_e32 v14, 1.0, v14
	v_add_f32_e32 v15, 1.0, v15
	v_add_f32_e32 v10, 1.0, v10
	v_add_f32_e32 v8, 1.0, v8
	v_add_f32_e32 v11, 1.0, v11
	v_add_f32_e32 v9, 1.0, v9
	v_rcp_f32_e32 v14, v14
	v_rcp_f32_e32 v15, v15
	v_rcp_f32_e32 v10, v10
	v_rcp_f32_e32 v8, v8
	v_rcp_f32_e32 v11, v11
	v_rcp_f32_e32 v9, v9
	v_mov_b32_e32 v12, v4
	v_mov_b32_e32 v13, v6
	v_mov_b32_e32 v6, v5
	v_pk_fma_f32 v[56:57], v[16:17], v[14:15], v[56:57]
	v_pk_fma_f32 v[0:1], v[12:13], v[10:11], v[0:1]
	v_pk_fma_f32 v[52:53], v[6:7], v[8:9], v[52:53]
	s_cbranch_scc0 .LBB0_21
	v_lshl_add_u32 v4, s27, 7, v2
	v_and_b32_sdwa v15, v120, v183 dst_sel:DWORD dst_unused:UNUSED_PAD src0_sel:WORD_1 src1_sel:DWORD
	v_or_b32_e32 v6, s12, v122
	v_ashrrev_i32_e32 v5, 31, v4
	v_readlane_b32 s12, v244, 7
	v_add3_u32 v16, v120, v15, s37
	v_and_b32_sdwa v15, v119, v183 dst_sel:DWORD dst_unused:UNUSED_PAD src0_sel:WORD_1 src1_sel:DWORD
	v_and_b32_sdwa v17, v118, v183 dst_sel:DWORD dst_unused:UNUSED_PAD src0_sel:WORD_1 src1_sel:DWORD
	v_or_b32_e32 v8, 48, v4
	v_ashrrev_i32_e32 v7, 31, v6
	v_or_b32_e32 v10, 16, v4
	v_or_b32_e32 v12, 32, v4
	v_lshlrev_b64 v[4:5], 11, v[4:5]
	v_readlane_b32 s13, v244, 8
	v_and_b32_sdwa v14, v121, v183 dst_sel:DWORD dst_unused:UNUSED_PAD src0_sel:WORD_1 src1_sel:DWORD
	v_add3_u32 v15, v119, v15, s37
	v_add3_u32 v17, v118, v17, s37
	v_lshl_add_u64 v[4:5], s[12:13], 0, v[4:5]
	v_lshlrev_b64 v[6:7], 1, v[6:7]
	v_add3_u32 v14, v121, v14, s37
	v_and_b32_e32 v15, 0xffff0000, v15
	v_and_b32_e32 v17, 0xffff0000, v17
	v_lshl_add_u64 v[4:5], v[4:5], 0, v[6:7]
	v_or_b32_sdwa v15, v15, v14 dst_sel:DWORD dst_unused:UNUSED_PAD src0_sel:DWORD src1_sel:WORD_1
	v_or_b32_sdwa v14, v17, v16 dst_sel:DWORD dst_unused:UNUSED_PAD src0_sel:DWORD src1_sel:WORD_1
	global_store_dwordx2 v[4:5], v[14:15], off
	v_and_b32_sdwa v15, v116, v183 dst_sel:DWORD dst_unused:UNUSED_PAD src0_sel:WORD_1 src1_sel:DWORD
	v_add3_u32 v16, v116, v15, s37
	v_and_b32_sdwa v15, v115, v183 dst_sel:DWORD dst_unused:UNUSED_PAD src0_sel:WORD_1 src1_sel:DWORD
	v_and_b32_sdwa v17, v114, v183 dst_sel:DWORD dst_unused:UNUSED_PAD src0_sel:WORD_1 src1_sel:DWORD
	v_and_b32_sdwa v14, v117, v183 dst_sel:DWORD dst_unused:UNUSED_PAD src0_sel:WORD_1 src1_sel:DWORD
	v_add3_u32 v15, v115, v15, s37
	v_add3_u32 v17, v114, v17, s37
	v_add3_u32 v14, v117, v14, s37
	v_and_b32_e32 v15, 0xffff0000, v15
	v_and_b32_e32 v17, 0xffff0000, v17
	v_or_b32_sdwa v15, v15, v14 dst_sel:DWORD dst_unused:UNUSED_PAD src0_sel:DWORD src1_sel:WORD_1
	v_or_b32_sdwa v14, v17, v16 dst_sel:DWORD dst_unused:UNUSED_PAD src0_sel:DWORD src1_sel:WORD_1
	global_store_dwordx2 v[4:5], v[14:15], off offset:32
	v_and_b32_sdwa v15, v112, v183 dst_sel:DWORD dst_unused:UNUSED_PAD src0_sel:WORD_1 src1_sel:DWORD
	v_add3_u32 v16, v112, v15, s37
	v_and_b32_sdwa v15, v109, v183 dst_sel:DWORD dst_unused:UNUSED_PAD src0_sel:WORD_1 src1_sel:DWORD
	v_and_b32_sdwa v17, v108, v183 dst_sel:DWORD dst_unused:UNUSED_PAD src0_sel:WORD_1 src1_sel:DWORD
; __device__ __forceinline__ unsigned pack2(float a, float b) { return (unsigned)f2bf(a) | ((unsigned)f2bf(b) << 16); }
; __device__ __forceinline__ void phase_gemm_merge(const Params& p, char* smem) {
;     ...
; #pragma unroll
;     for (int i = 0; i < 4; ++i) {
;       const int m = mt * 128 + wm * 64 + i * 16 + (lane & 15);
; #pragma unroll
;       for (int j = 0; j < 4; ++j) {
;         const int n = nt * 128 + wn * 64 + j * 16 + (lane >> 4) * 4;
;         uint2 o;
;         o.x = pack2(outv[i][j][0], outv[i][j][1]);
;         o.y = pack2(outv[i][j][2], outv[i][j][3]);
;         *(uint2*)(MG + (size_t)m * 1024 + n) = o;
;       }
;     }
	v_and_b32_sdwa v14, v113, v183 dst_sel:DWORD dst_unused:UNUSED_PAD src0_sel:WORD_1 src1_sel:DWORD
	v_add3_u32 v15, v109, v15, s37
	v_add3_u32 v17, v108, v17, s37
	v_add3_u32 v14, v113, v14, s37
	v_and_b32_e32 v15, 0xffff0000, v15
	v_and_b32_e32 v17, 0xffff0000, v17
	v_or_b32_sdwa v15, v15, v14 dst_sel:DWORD dst_unused:UNUSED_PAD src0_sel:DWORD src1_sel:WORD_1
	v_or_b32_sdwa v14, v17, v16 dst_sel:DWORD dst_unused:UNUSED_PAD src0_sel:DWORD src1_sel:WORD_1
	global_store_dwordx2 v[4:5], v[14:15], off offset:64
	v_and_b32_sdwa v15, v100, v183 dst_sel:DWORD dst_unused:UNUSED_PAD src0_sel:WORD_1 src1_sel:DWORD
	v_add3_u32 v16, v100, v15, s37
	v_and_b32_sdwa v15, v99, v183 dst_sel:DWORD dst_unused:UNUSED_PAD src0_sel:WORD_1 src1_sel:DWORD
	v_and_b32_sdwa v17, v98, v183 dst_sel:DWORD dst_unused:UNUSED_PAD src0_sel:WORD_1 src1_sel:DWORD
	v_and_b32_sdwa v14, v101, v183 dst_sel:DWORD dst_unused:UNUSED_PAD src0_sel:WORD_1 src1_sel:DWORD
	v_add3_u32 v15, v99, v15, s37
	v_add3_u32 v17, v98, v17, s37
	v_add3_u32 v14, v101, v14, s37
	v_and_b32_e32 v15, 0xffff0000, v15
	v_and_b32_e32 v17, 0xffff0000, v17
	v_ashrrev_i32_e32 v11, 31, v10
	v_or_b32_sdwa v15, v15, v14 dst_sel:DWORD dst_unused:UNUSED_PAD src0_sel:DWORD src1_sel:WORD_1
	v_or_b32_sdwa v14, v17, v16 dst_sel:DWORD dst_unused:UNUSED_PAD src0_sel:DWORD src1_sel:WORD_1
	global_store_dwordx2 v[4:5], v[14:15], off offset:96
	v_lshlrev_b64 v[4:5], 11, v[10:11]
	v_and_b32_sdwa v11, v96, v183 dst_sel:DWORD dst_unused:UNUSED_PAD src0_sel:WORD_1 src1_sel:DWORD
	v_add3_u32 v14, v96, v11, s37
	v_and_b32_sdwa v11, v95, v183 dst_sel:DWORD dst_unused:UNUSED_PAD src0_sel:WORD_1 src1_sel:DWORD
	v_and_b32_sdwa v15, v94, v183 dst_sel:DWORD dst_unused:UNUSED_PAD src0_sel:WORD_1 src1_sel:DWORD
	v_and_b32_sdwa v10, v97, v183 dst_sel:DWORD dst_unused:UNUSED_PAD src0_sel:WORD_1 src1_sel:DWORD
	v_add3_u32 v11, v95, v11, s37
	v_add3_u32 v15, v94, v15, s37
	v_lshl_add_u64 v[4:5], s[12:13], 0, v[4:5]
	v_add3_u32 v10, v97, v10, s37
	v_and_b32_e32 v11, 0xffff0000, v11
	v_and_b32_e32 v15, 0xffff0000, v15
	v_lshl_add_u64 v[4:5], v[4:5], 0, v[6:7]
	v_or_b32_sdwa v11, v11, v10 dst_sel:DWORD dst_unused:UNUSED_PAD src0_sel:DWORD src1_sel:WORD_1
	v_or_b32_sdwa v10, v15, v14 dst_sel:DWORD dst_unused:UNUSED_PAD src0_sel:DWORD src1_sel:WORD_1
	global_store_dwordx2 v[4:5], v[10:11], off
	v_and_b32_sdwa v11, v92, v183 dst_sel:DWORD dst_unused:UNUSED_PAD src0_sel:WORD_1 src1_sel:DWORD
	v_add3_u32 v14, v92, v11, s37
	v_and_b32_sdwa v11, v91, v183 dst_sel:DWORD dst_unused:UNUSED_PAD src0_sel:WORD_1 src1_sel:DWORD
	v_and_b32_sdwa v15, v90, v183 dst_sel:DWORD dst_unused:UNUSED_PAD src0_sel:WORD_1 src1_sel:DWORD
	v_and_b32_sdwa v10, v93, v183 dst_sel:DWORD dst_unused:UNUSED_PAD src0_sel:WORD_1 src1_sel:DWORD
	v_add3_u32 v11, v91, v11, s37
	v_add3_u32 v15, v90, v15, s37
	v_add3_u32 v10, v93, v10, s37
	v_and_b32_e32 v11, 0xffff0000, v11
	v_and_b32_e32 v15, 0xffff0000, v15
	v_or_b32_sdwa v11, v11, v10 dst_sel:DWORD dst_unused:UNUSED_PAD src0_sel:DWORD src1_sel:WORD_1
	v_or_b32_sdwa v10, v15, v14 dst_sel:DWORD dst_unused:UNUSED_PAD src0_sel:DWORD src1_sel:WORD_1
	global_store_dwordx2 v[4:5], v[10:11], off offset:32
	v_and_b32_sdwa v11, v88, v183 dst_sel:DWORD dst_unused:UNUSED_PAD src0_sel:WORD_1 src1_sel:DWORD
	v_add3_u32 v14, v88, v11, s37
	v_and_b32_sdwa v11, v87, v183 dst_sel:DWORD dst_unused:UNUSED_PAD src0_sel:WORD_1 src1_sel:DWORD
	v_and_b32_sdwa v15, v86, v183 dst_sel:DWORD dst_unused:UNUSED_PAD src0_sel:WORD_1 src1_sel:DWORD
	v_and_b32_sdwa v10, v89, v183 dst_sel:DWORD dst_unused:UNUSED_PAD src0_sel:WORD_1 src1_sel:DWORD
	v_add3_u32 v11, v87, v11, s37
	v_add3_u32 v15, v86, v15, s37
	v_add3_u32 v10, v89, v10, s37
	v_and_b32_e32 v11, 0xffff0000, v11
	v_and_b32_e32 v15, 0xffff0000, v15
	v_or_b32_sdwa v11, v11, v10 dst_sel:DWORD dst_unused:UNUSED_PAD src0_sel:DWORD src1_sel:WORD_1
	v_or_b32_sdwa v10, v15, v14 dst_sel:DWORD dst_unused:UNUSED_PAD src0_sel:DWORD src1_sel:WORD_1
	global_store_dwordx2 v[4:5], v[10:11], off offset:64
	v_and_b32_sdwa v11, v84, v183 dst_sel:DWORD dst_unused:UNUSED_PAD src0_sel:WORD_1 src1_sel:DWORD
	v_add3_u32 v14, v84, v11, s37
	v_and_b32_sdwa v11, v83, v183 dst_sel:DWORD dst_unused:UNUSED_PAD src0_sel:WORD_1 src1_sel:DWORD
	v_and_b32_sdwa v15, v82, v183 dst_sel:DWORD dst_unused:UNUSED_PAD src0_sel:WORD_1 src1_sel:DWORD
	v_and_b32_sdwa v10, v85, v183 dst_sel:DWORD dst_unused:UNUSED_PAD src0_sel:WORD_1 src1_sel:DWORD
	v_add3_u32 v11, v83, v11, s37
	v_add3_u32 v15, v82, v15, s37
	v_add3_u32 v10, v85, v10, s37
	v_and_b32_e32 v11, 0xffff0000, v11
	v_and_b32_e32 v15, 0xffff0000, v15
	v_or_b32_sdwa v11, v11, v10 dst_sel:DWORD dst_unused:UNUSED_PAD src0_sel:DWORD src1_sel:WORD_1
	v_or_b32_sdwa v10, v15, v14 dst_sel:DWORD dst_unused:UNUSED_PAD src0_sel:DWORD src1_sel:WORD_1
	v_ashrrev_i32_e32 v13, 31, v12
	global_store_dwordx2 v[4:5], v[10:11], off offset:96
	v_and_b32_sdwa v11, v80, v183 dst_sel:DWORD dst_unused:UNUSED_PAD src0_sel:WORD_1 src1_sel:DWORD
	v_lshlrev_b64 v[4:5], 11, v[12:13]
	v_add3_u32 v12, v80, v11, s37
	v_and_b32_sdwa v11, v79, v183 dst_sel:DWORD dst_unused:UNUSED_PAD src0_sel:WORD_1 src1_sel:DWORD
	v_and_b32_sdwa v13, v78, v183 dst_sel:DWORD dst_unused:UNUSED_PAD src0_sel:WORD_1 src1_sel:DWORD
	v_and_b32_sdwa v10, v81, v183 dst_sel:DWORD dst_unused:UNUSED_PAD src0_sel:WORD_1 src1_sel:DWORD
	v_add3_u32 v11, v79, v11, s37
	v_add3_u32 v13, v78, v13, s37
	v_lshl_add_u64 v[4:5], s[12:13], 0, v[4:5]
	v_add3_u32 v10, v81, v10, s37
	v_and_b32_e32 v11, 0xffff0000, v11
	v_and_b32_e32 v13, 0xffff0000, v13
	v_lshl_add_u64 v[4:5], v[4:5], 0, v[6:7]
	v_or_b32_sdwa v11, v11, v10 dst_sel:DWORD dst_unused:UNUSED_PAD src0_sel:DWORD src1_sel:WORD_1
; __device__ __forceinline__ unsigned pack2(float a, float b) { return (unsigned)f2bf(a) | ((unsigned)f2bf(b) << 16); }
; __device__ __forceinline__ void phase_gemm_merge(const Params& p, char* smem) {
;     ...
; #pragma unroll
;     for (int i = 0; i < 4; ++i) {
;       const int m = mt * 128 + wm * 64 + i * 16 + (lane & 15);
; #pragma unroll
;       for (int j = 0; j < 4; ++j) {
;         const int n = nt * 128 + wn * 64 + j * 16 + (lane >> 4) * 4;
;         uint2 o;
;         o.x = pack2(outv[i][j][0], outv[i][j][1]);
;         o.y = pack2(outv[i][j][2], outv[i][j][3]);
;         *(uint2*)(MG + (size_t)m * 1024 + n) = o;
;       }
;     }
	v_or_b32_sdwa v10, v13, v12 dst_sel:DWORD dst_unused:UNUSED_PAD src0_sel:DWORD src1_sel:WORD_1
	global_store_dwordx2 v[4:5], v[10:11], off
	v_and_b32_sdwa v11, v76, v183 dst_sel:DWORD dst_unused:UNUSED_PAD src0_sel:WORD_1 src1_sel:DWORD
	v_add3_u32 v12, v76, v11, s37
	v_and_b32_sdwa v11, v75, v183 dst_sel:DWORD dst_unused:UNUSED_PAD src0_sel:WORD_1 src1_sel:DWORD
	v_and_b32_sdwa v13, v74, v183 dst_sel:DWORD dst_unused:UNUSED_PAD src0_sel:WORD_1 src1_sel:DWORD
	v_and_b32_sdwa v10, v77, v183 dst_sel:DWORD dst_unused:UNUSED_PAD src0_sel:WORD_1 src1_sel:DWORD
	v_add3_u32 v11, v75, v11, s37
	v_add3_u32 v13, v74, v13, s37
	v_add3_u32 v10, v77, v10, s37
	v_and_b32_e32 v11, 0xffff0000, v11
	v_and_b32_e32 v13, 0xffff0000, v13
	v_or_b32_sdwa v11, v11, v10 dst_sel:DWORD dst_unused:UNUSED_PAD src0_sel:DWORD src1_sel:WORD_1
	v_or_b32_sdwa v10, v13, v12 dst_sel:DWORD dst_unused:UNUSED_PAD src0_sel:DWORD src1_sel:WORD_1
	global_store_dwordx2 v[4:5], v[10:11], off offset:32
	v_and_b32_sdwa v11, v72, v183 dst_sel:DWORD dst_unused:UNUSED_PAD src0_sel:WORD_1 src1_sel:DWORD
	v_add3_u32 v12, v72, v11, s37
	v_and_b32_sdwa v11, v71, v183 dst_sel:DWORD dst_unused:UNUSED_PAD src0_sel:WORD_1 src1_sel:DWORD
	v_and_b32_sdwa v13, v70, v183 dst_sel:DWORD dst_unused:UNUSED_PAD src0_sel:WORD_1 src1_sel:DWORD
	v_and_b32_sdwa v10, v73, v183 dst_sel:DWORD dst_unused:UNUSED_PAD src0_sel:WORD_1 src1_sel:DWORD
	v_add3_u32 v11, v71, v11, s37
	v_add3_u32 v13, v70, v13, s37
	v_add3_u32 v10, v73, v10, s37
	v_and_b32_e32 v11, 0xffff0000, v11
	v_and_b32_e32 v13, 0xffff0000, v13
	v_or_b32_sdwa v11, v11, v10 dst_sel:DWORD dst_unused:UNUSED_PAD src0_sel:DWORD src1_sel:WORD_1
	v_or_b32_sdwa v10, v13, v12 dst_sel:DWORD dst_unused:UNUSED_PAD src0_sel:DWORD src1_sel:WORD_1
	global_store_dwordx2 v[4:5], v[10:11], off offset:64
	v_and_b32_sdwa v11, v68, v183 dst_sel:DWORD dst_unused:UNUSED_PAD src0_sel:WORD_1 src1_sel:DWORD
	v_add3_u32 v12, v68, v11, s37
	v_and_b32_sdwa v11, v67, v183 dst_sel:DWORD dst_unused:UNUSED_PAD src0_sel:WORD_1 src1_sel:DWORD
	v_and_b32_sdwa v13, v66, v183 dst_sel:DWORD dst_unused:UNUSED_PAD src0_sel:WORD_1 src1_sel:DWORD
	v_and_b32_sdwa v10, v69, v183 dst_sel:DWORD dst_unused:UNUSED_PAD src0_sel:WORD_1 src1_sel:DWORD
	v_add3_u32 v11, v67, v11, s37
	v_add3_u32 v13, v66, v13, s37
	v_add3_u32 v10, v69, v10, s37
	v_and_b32_e32 v11, 0xffff0000, v11
	v_and_b32_e32 v13, 0xffff0000, v13
	v_ashrrev_i32_e32 v9, 31, v8
	v_or_b32_sdwa v11, v11, v10 dst_sel:DWORD dst_unused:UNUSED_PAD src0_sel:DWORD src1_sel:WORD_1
	v_or_b32_sdwa v10, v13, v12 dst_sel:DWORD dst_unused:UNUSED_PAD src0_sel:DWORD src1_sel:WORD_1
	global_store_dwordx2 v[4:5], v[10:11], off offset:96
	v_lshlrev_b64 v[4:5], 11, v[8:9]
	v_lshl_add_u64 v[4:5], s[12:13], 0, v[4:5]
	v_lshl_add_u64 v[4:5], v[4:5], 0, v[6:7]
	v_and_b32_sdwa v7, v64, v183 dst_sel:DWORD dst_unused:UNUSED_PAD src0_sel:WORD_1 src1_sel:DWORD
	v_add3_u32 v8, v64, v7, s37
	v_and_b32_sdwa v7, v63, v183 dst_sel:DWORD dst_unused:UNUSED_PAD src0_sel:WORD_1 src1_sel:DWORD
	v_and_b32_sdwa v9, v62, v183 dst_sel:DWORD dst_unused:UNUSED_PAD src0_sel:WORD_1 src1_sel:DWORD
	v_and_b32_sdwa v6, v65, v183 dst_sel:DWORD dst_unused:UNUSED_PAD src0_sel:WORD_1 src1_sel:DWORD
	v_add3_u32 v7, v63, v7, s37
	v_add3_u32 v9, v62, v9, s37
	v_add3_u32 v6, v65, v6, s37
	v_and_b32_e32 v7, 0xffff0000, v7
	v_and_b32_e32 v9, 0xffff0000, v9
	v_or_b32_sdwa v7, v7, v6 dst_sel:DWORD dst_unused:UNUSED_PAD src0_sel:DWORD src1_sel:WORD_1
	v_or_b32_sdwa v6, v9, v8 dst_sel:DWORD dst_unused:UNUSED_PAD src0_sel:DWORD src1_sel:WORD_1
	global_store_dwordx2 v[4:5], v[6:7], off
	v_and_b32_sdwa v7, v60, v183 dst_sel:DWORD dst_unused:UNUSED_PAD src0_sel:WORD_1 src1_sel:DWORD
	v_add3_u32 v8, v60, v7, s37
	v_and_b32_sdwa v7, v59, v183 dst_sel:DWORD dst_unused:UNUSED_PAD src0_sel:WORD_1 src1_sel:DWORD
	v_and_b32_sdwa v9, v58, v183 dst_sel:DWORD dst_unused:UNUSED_PAD src0_sel:WORD_1 src1_sel:DWORD
	v_and_b32_sdwa v6, v61, v183 dst_sel:DWORD dst_unused:UNUSED_PAD src0_sel:WORD_1 src1_sel:DWORD
	v_add3_u32 v7, v59, v7, s37
	v_add3_u32 v9, v58, v9, s37
	v_add3_u32 v6, v61, v6, s37
	v_and_b32_e32 v7, 0xffff0000, v7
	v_and_b32_e32 v9, 0xffff0000, v9
	v_or_b32_sdwa v7, v7, v6 dst_sel:DWORD dst_unused:UNUSED_PAD src0_sel:DWORD src1_sel:WORD_1
	v_or_b32_sdwa v6, v9, v8 dst_sel:DWORD dst_unused:UNUSED_PAD src0_sel:DWORD src1_sel:WORD_1
	global_store_dwordx2 v[4:5], v[6:7], off offset:32
	v_and_b32_sdwa v7, v56, v183 dst_sel:DWORD dst_unused:UNUSED_PAD src0_sel:WORD_1 src1_sel:DWORD
	v_add3_u32 v8, v56, v7, s37
	v_and_b32_sdwa v7, v55, v183 dst_sel:DWORD dst_unused:UNUSED_PAD src0_sel:WORD_1 src1_sel:DWORD
	v_and_b32_sdwa v9, v54, v183 dst_sel:DWORD dst_unused:UNUSED_PAD src0_sel:WORD_1 src1_sel:DWORD
	v_and_b32_sdwa v6, v57, v183 dst_sel:DWORD dst_unused:UNUSED_PAD src0_sel:WORD_1 src1_sel:DWORD
	v_add3_u32 v7, v55, v7, s37
	v_add3_u32 v9, v54, v9, s37
	v_add3_u32 v6, v57, v6, s37
	v_and_b32_e32 v7, 0xffff0000, v7
	v_and_b32_e32 v9, 0xffff0000, v9
	v_or_b32_sdwa v7, v7, v6 dst_sel:DWORD dst_unused:UNUSED_PAD src0_sel:DWORD src1_sel:WORD_1
	v_or_b32_sdwa v6, v9, v8 dst_sel:DWORD dst_unused:UNUSED_PAD src0_sel:DWORD src1_sel:WORD_1
	global_store_dwordx2 v[4:5], v[6:7], off offset:64
	v_and_b32_sdwa v6, v1, v183 dst_sel:DWORD dst_unused:UNUSED_PAD src0_sel:WORD_1 src1_sel:DWORD
	v_and_b32_sdwa v7, v0, v183 dst_sel:DWORD dst_unused:UNUSED_PAD src0_sel:WORD_1 src1_sel:DWORD
	v_add3_u32 v0, v0, v7, s37
	v_add3_u32 v1, v1, v6, s37
	v_and_b32_sdwa v6, v53, v183 dst_sel:DWORD dst_unused:UNUSED_PAD src0_sel:WORD_1 src1_sel:DWORD
	v_and_b32_sdwa v7, v52, v183 dst_sel:DWORD dst_unused:UNUSED_PAD src0_sel:WORD_1 src1_sel:DWORD
	v_add3_u32 v6, v53, v6, s37
	v_add3_u32 v7, v52, v7, s37
	s_add_i32 s24, s24, 1
	v_and_b32_e32 v6, 0xffff0000, v6
	v_and_b32_e32 v7, 0xffff0000, v7
	s_cmp_eq_u32 s24, s22
	v_or_b32_sdwa v1, v6, v1 dst_sel:DWORD dst_unused:UNUSED_PAD src0_sel:DWORD src1_sel:WORD_1
	v_or_b32_sdwa v0, v7, v0 dst_sel:DWORD dst_unused:UNUSED_PAD src0_sel:DWORD src1_sel:WORD_1
	s_cselect_b64 s[12:13], -1, 0
	s_mov_b32 s31, 0x18000
	global_store_dwordx2 v[4:5], v[0:1], off offset:96
	s_branch .LBB0_18
